# GEMM K-loops: B-fragment LDS read addresses folded into ds_read immediates (4 fewer VALU per iteration in load segments)
# baseline (speedup 1.0000x reference)
;     __host__ __device__ bool next(int i, Unit& u) const { if (!base.next(i >> 1, u)) return false; if (i & 1) { u.pm += 64; u.pn += 8; } return true; }
; #define PG8_STAGE(bufoff, gbase, voff) do { _Pragma("unroll") for (int _i = 0; _i < 2; ++_i) \
;         __builtin_amdgcn_global_load_lds((const unsigned*)((const char*)(gbase) + (voff)[_i]), (PG8_LAS unsigned*)(lds + (bufoff) + ldsw + _i * 8192), 16, 0, 0); } while (0)
; #define PG8_LDA(dst, b, h) do { _Pragma("unroll") for (int m = 0; m < 4; ++m) _Pragma("unroll") for (int k = 0; k < 2; ++k) dst[m][k] = *(const PG8_LAS bf16x8*)(lds + PG8_SA(b, h) + aoff + m * 2048 + k * 1024); } while (0)
; #define PG8_LDB(dst, b, h) do { _Pragma("unroll") for (int n = 0; n < 2; ++n) _Pragma("unroll") for (int k = 0; k < 2; ++k) dst[n][k] = *(const PG8_LAS bf16x8*)(lds + PG8_SB(b, h) + boff + n * 2048 + k * 1024); } while (0)
; #define PG8_WAIT_V(n) asm volatile("s_waitcnt vmcnt(" #n ")" ::: "memory")
; #define PG8_BAR __builtin_amdgcn_s_barrier()
; template <class Epi, class Sched, bool ALIGN_EPI = false, bool SP2 = false>
; __device__ __forceinline__ void gemm_phase(PG8_LAS unsigned char* lds, const Gemm g, const Sched& S, const Epi& E) {
;     ...
;         const bool has_next = S.next(ui + 1, nxt);
;         const char* nA = has_next ? (const char*)g.A + (size_t)nxt.pm * tstep : cA; const char* nB = has_next ? (const char*)g.Bt + (size_t)nxt.pn * tstep : cB;
;         for (int t = 0; t < nt; t += 2) {
;             const bool last = (t == nt - 2);
;             const char* a1 = cA + (size_t)(t + 1) * kstep;
;             const char* a2 = last ? nA : cA + (size_t)(t + 2) * kstep; const char* b2 = last ? nB : cB + (size_t)(t + 2) * kstep;
;             const char* a3 = a2 + kstep; const char* b3 = b2 + kstep;
;             if (last && has_next) S.a_ready(nxt);
;             if constexpr (SP2) {
;             PG8_LDB(B0, 0, 0); PG8_LDB(B1, 0, 1); PG8_SCHED; PG8_LDA(At, 0, 0); PG8_STAGE(PG8_SA(1, 1), a1 + hstep, voffA);
;             PG8_WAIT_V(8); PG8_WAIT_L(0); PG8_BAR; PG8_MMA(0, 0, At, B0); PG8_MMA(0, 1, At, B1); PG8_BAR; PG8_SCHED;
;     ...
;         for (int a = 0; a < 2; ++a)
; #pragma unroll
;             for (int b = 0; b < 2; ++b)
; #pragma unroll
;                 for (int m = 0; m < 4; ++m)
; #pragma unroll
;                     for (int n = 0; n < 2; ++n) acc[a][b][m][n] = (f32x4){0.f, 0.f, 0.f, 0.f};
.LBB0_24:
	s_ashr_i32 s55, s54, 31
	s_lshl_b64 s[76:77], s[54:55], 20
	s_add_u32 s76, s8, s76
	s_addc_u32 s77, s9, s77
	s_and_b64 s[78:79], s[74:75], exec
	s_cselect_b32 s55, s77, s53
	s_cselect_b32 s83, s76, s52
	s_ashr_i32 s73, s72, 31
	s_lshl_b64 s[78:79], s[72:73], 20
	s_add_u32 s78, s0, s78
	s_addc_u32 s79, s1, s79
	s_and_b64 s[80:81], s[74:75], exec
	s_cselect_b32 s73, s79, s5
	s_cselect_b32 s84, s78, s4
	s_add_u32 s80, s52, 0x80080
	s_addc_u32 s81, s53, 0
	s_add_u32 s85, s4, 0x100
	v_mov_b32_e32 v0, 0
	s_addc_u32 s86, s5, 0
	s_mov_b32 s87, -2
	v_add_u32_e32 v200, 0x10000, v139
	v_mov_b32_e32 v1, v0
	v_mov_b32_e32 v2, v0
	v_mov_b32_e32 v3, v0
	v_mov_b32_e32 v4, v0
	v_mov_b32_e32 v5, v0
	v_mov_b32_e32 v6, v0
	v_mov_b32_e32 v7, v0
	v_mov_b32_e32 v8, v0
	v_mov_b32_e32 v9, v0
	v_mov_b32_e32 v10, v0
	v_mov_b32_e32 v11, v0
	v_mov_b32_e32 v12, v0
	v_mov_b32_e32 v13, v0
	v_mov_b32_e32 v14, v0
	v_mov_b32_e32 v15, v0
	v_mov_b32_e32 v24, v0
	v_mov_b32_e32 v25, v0
	v_mov_b32_e32 v26, v0
	v_mov_b32_e32 v27, v0
	v_mov_b32_e32 v28, v0
	v_mov_b32_e32 v29, v0
	v_mov_b32_e32 v30, v0
	v_mov_b32_e32 v31, v0
	v_mov_b32_e32 v40, v0
	v_mov_b32_e32 v41, v0
	v_mov_b32_e32 v42, v0
	v_mov_b32_e32 v43, v0
	v_mov_b32_e32 v44, v0
	v_mov_b32_e32 v45, v0
	v_mov_b32_e32 v46, v0
	v_mov_b32_e32 v47, v0
	v_mov_b32_e32 v16, v0
	v_mov_b32_e32 v17, v0
	v_mov_b32_e32 v18, v0
	v_mov_b32_e32 v19, v0
	v_mov_b32_e32 v20, v0
	v_mov_b32_e32 v21, v0
	v_mov_b32_e32 v22, v0
	v_mov_b32_e32 v23, v0
	v_mov_b32_e32 v32, v0
	v_mov_b32_e32 v33, v0
	v_mov_b32_e32 v34, v0
	v_mov_b32_e32 v35, v0
	v_mov_b32_e32 v36, v0
	v_mov_b32_e32 v37, v0
	v_mov_b32_e32 v38, v0
	v_mov_b32_e32 v39, v0
	v_mov_b32_e32 v48, v0
	v_mov_b32_e32 v49, v0
	v_mov_b32_e32 v50, v0
	v_mov_b32_e32 v51, v0
	v_mov_b32_e32 v52, v0
	v_mov_b32_e32 v53, v0
	v_mov_b32_e32 v54, v0
	v_mov_b32_e32 v55, v0
	v_mov_b32_e32 v56, v0
	v_mov_b32_e32 v57, v0
	v_mov_b32_e32 v58, v0
	v_mov_b32_e32 v59, v0
	v_mov_b32_e32 v60, v0
	v_mov_b32_e32 v61, v0
	v_mov_b32_e32 v62, v0
	v_mov_b32_e32 v63, v0
	v_mov_b32_e32 v64, v0
	v_mov_b32_e32 v65, v0
	v_mov_b32_e32 v66, v0
	v_mov_b32_e32 v67, v0
	v_mov_b32_e32 v68, v0
	v_mov_b32_e32 v69, v0
	v_mov_b32_e32 v70, v0
	v_mov_b32_e32 v71, v0
	v_mov_b32_e32 v72, v0
	v_mov_b32_e32 v73, v0
	v_mov_b32_e32 v74, v0
	v_mov_b32_e32 v75, v0
	v_mov_b32_e32 v76, v0
	v_mov_b32_e32 v77, v0
	v_mov_b32_e32 v78, v0
	v_mov_b32_e32 v79, v0
	v_mov_b32_e32 v88, v0
	v_mov_b32_e32 v89, v0
	v_mov_b32_e32 v90, v0
	v_mov_b32_e32 v91, v0
	v_mov_b32_e32 v92, v0
	v_mov_b32_e32 v93, v0
	v_mov_b32_e32 v94, v0
	v_mov_b32_e32 v95, v0
	v_mov_b32_e32 v104, v0
	v_mov_b32_e32 v105, v0
	v_mov_b32_e32 v106, v0
	v_mov_b32_e32 v107, v0
	v_mov_b32_e32 v108, v0
	v_mov_b32_e32 v109, v0
	v_mov_b32_e32 v110, v0
	v_mov_b32_e32 v111, v0
	v_mov_b32_e32 v80, v0
	v_mov_b32_e32 v81, v0
	v_mov_b32_e32 v82, v0
	v_mov_b32_e32 v83, v0
	v_mov_b32_e32 v84, v0
	v_mov_b32_e32 v85, v0
	v_mov_b32_e32 v86, v0
	v_mov_b32_e32 v87, v0
	v_mov_b32_e32 v96, v0
	v_mov_b32_e32 v97, v0
	v_mov_b32_e32 v98, v0
	v_mov_b32_e32 v99, v0
	v_mov_b32_e32 v100, v0
	v_mov_b32_e32 v101, v0
	v_mov_b32_e32 v102, v0
	v_mov_b32_e32 v103, v0
	v_mov_b32_e32 v112, v0
	v_mov_b32_e32 v113, v0
	v_mov_b32_e32 v114, v0
	v_mov_b32_e32 v115, v0
	v_mov_b32_e32 v116, v0
	v_mov_b32_e32 v117, v0
	v_mov_b32_e32 v118, v0
	v_mov_b32_e32 v119, v0
	v_mov_b32_e32 v120, v0
	v_mov_b32_e32 v121, v0
	v_mov_b32_e32 v122, v0
	v_mov_b32_e32 v123, v0
	v_mov_b32_e32 v124, v0
	v_mov_b32_e32 v125, v0
	v_mov_b32_e32 v126, v0
	v_mov_b32_e32 v127, v0
.LBB0_25:
	s_add_i32 s88, 0, 0x10000
	s_add_i32 s90, 0, 0x14000
	ds_read_b128 v[142:145], v200
	ds_read_b128 v[146:149], v200 offset:1024
	ds_read_b128 v[150:153], v200 offset:2048
	ds_read_b128 v[154:157], v200 offset:3072
	ds_read_b128 v[164:167], v200 offset:16384
	ds_read_b128 v[168:171], v200 offset:17408
	ds_read_b128 v[172:175], v200 offset:18432
	ds_read_b128 v[176:179], v200 offset:19456
	s_add_i32 m0, s29, 0xc000
	ds_read_b128 v[180:183], v141
	ds_read_b128 v[184:187], v141 offset:1024
	ds_read_b128 v[188:191], v141 offset:2048
	ds_read_b128 v[192:195], v141 offset:3072
	ds_read_b128 v[196:199], v141 offset:4096
	ds_read_b128 v[222:225], v141 offset:5120
	ds_read_b128 v[226:229], v141 offset:6144
	ds_read_b128 v[230:233], v141 offset:7168
	global_load_lds_dwordx4 v134, s[80:81]
	s_add_i32 m0, s29, 0xe000
	s_nop 0
	global_load_lds_dwordx4 v136, s[80:81]
	s_add_u32 s4, s80, 0xfff80080
	s_addc_u32 s5, s81, -1
	s_cmp_eq_u32 s87, 28
	s_cselect_b32 s53, s55, s5
	s_cselect_b32 s52, s83, s4
	s_cselect_b32 s5, s73, s86
	s_cselect_b32 s4, s84, s85
	s_waitcnt vmcnt(8)
	s_waitcnt lgkmcnt(0)
	s_barrier
; #define PG8_STAGE(bufoff, gbase, voff) do { _Pragma("unroll") for (int _i = 0; _i < 2; ++_i) \
;         __builtin_amdgcn_global_load_lds((const unsigned*)((const char*)(gbase) + (voff)[_i]), (PG8_LAS unsigned*)(lds + (bufoff) + ldsw + _i * 8192), 16, 0, 0); } while (0)
; #define PG8_LDA(dst, b, h) do { _Pragma("unroll") for (int m = 0; m < 4; ++m) _Pragma("unroll") for (int k = 0; k < 2; ++k) dst[m][k] = *(const PG8_LAS bf16x8*)(lds + PG8_SA(b, h) + aoff + m * 2048 + k * 1024); } while (0)
; #define PG8_MMA(ai, bj, At, Bt) do { __builtin_amdgcn_s_setprio(1); _Pragma("unroll") for (int m = 0; m < 4; ++m) _Pragma("unroll") for (int n = 0; n < 2; ++n) _Pragma("unroll") for (int k = 0; k < 2; ++k) \
;         acc[ai][bj][m][n] = __builtin_amdgcn_mfma_f32_16x16x32_bf16(Bt[n][k], At[m][k], acc[ai][bj][m][n], 0, 0, 0); __builtin_amdgcn_s_setprio(0); } while (0)
; #define PG8_WAIT_V(n) asm volatile("s_waitcnt vmcnt(" #n ")" ::: "memory")
; #define PG8_WAIT_L(n) asm volatile("s_waitcnt lgkmcnt(" #n ")" ::: "memory")
; #define PG8_BAR __builtin_amdgcn_s_barrier()
; #define PG8_SCHED __builtin_amdgcn_sched_barrier(0)
; template <class Epi, class Sched, bool ALIGN_EPI = false, bool SP2 = false>
; __device__ __forceinline__ void gemm_phase(PG8_LAS unsigned char* lds, const Gemm g, const Sched& S, const Epi& E) {
;     ...
;             PG8_WAIT_V(8); PG8_WAIT_L(0); PG8_BAR; PG8_MMA(0, 0, At, B0); PG8_MMA(0, 1, At, B1); PG8_BAR; PG8_SCHED;
;             PG8_LDA(At, 0, 1); PG8_STAGE(PG8_SB(0, 0), b2, voffB); PG8_STAGE(PG8_SB(0, 1), b2 + hstep, voffB); PG8_STAGE(PG8_SA(0, 0), a2, voffA);
;             PG8_WAIT_V(8); PG8_WAIT_L(0); PG8_BAR; PG8_MMA(1, 0, At, B0); PG8_MMA(1, 1, At, B1); PG8_BAR; PG8_SCHED;
	s_setprio 1
	s_waitcnt lgkmcnt(0)
	v_mfma_f32_16x16x32_bf16 v[124:127], v[142:145], v[180:183], v[124:127]
	v_mfma_f32_16x16x32_bf16 v[120:123], v[150:153], v[180:183], v[120:123]
	v_mfma_f32_16x16x32_bf16 v[116:119], v[142:145], v[188:191], v[116:119]
	v_mfma_f32_16x16x32_bf16 v[112:115], v[150:153], v[188:191], v[112:115]
	v_mfma_f32_16x16x32_bf16 v[100:103], v[142:145], v[196:199], v[100:103]
	v_mfma_f32_16x16x32_bf16 v[96:99], v[150:153], v[196:199], v[96:99]
	v_mfma_f32_16x16x32_bf16 v[84:87], v[142:145], v[226:229], v[84:87]
	v_mfma_f32_16x16x32_bf16 v[80:83], v[150:153], v[226:229], v[80:83]
	v_mfma_f32_16x16x32_bf16 v[124:127], v[146:149], v[184:187], v[124:127]
	v_mfma_f32_16x16x32_bf16 v[120:123], v[154:157], v[184:187], v[120:123]
	v_mfma_f32_16x16x32_bf16 v[116:119], v[146:149], v[192:195], v[116:119]
	v_mfma_f32_16x16x32_bf16 v[112:115], v[154:157], v[192:195], v[112:115]
	v_mfma_f32_16x16x32_bf16 v[100:103], v[146:149], v[222:225], v[100:103]
	v_mfma_f32_16x16x32_bf16 v[96:99], v[154:157], v[222:225], v[96:99]
	v_mfma_f32_16x16x32_bf16 v[84:87], v[146:149], v[230:233], v[84:87]
	v_mfma_f32_16x16x32_bf16 v[80:83], v[154:157], v[230:233], v[80:83]
	s_setprio 0
	s_setprio 1
	v_mfma_f32_16x16x32_bf16 v[108:111], v[164:167], v[180:183], v[108:111]
	v_mfma_f32_16x16x32_bf16 v[104:107], v[172:175], v[180:183], v[104:107]
	v_mfma_f32_16x16x32_bf16 v[92:95], v[164:167], v[188:191], v[92:95]
	v_mfma_f32_16x16x32_bf16 v[88:91], v[172:175], v[188:191], v[88:91]
	v_mfma_f32_16x16x32_bf16 v[76:79], v[164:167], v[196:199], v[76:79]
	v_mfma_f32_16x16x32_bf16 v[72:75], v[172:175], v[196:199], v[72:75]
	v_mfma_f32_16x16x32_bf16 v[68:71], v[164:167], v[226:229], v[68:71]
	v_mfma_f32_16x16x32_bf16 v[64:67], v[172:175], v[226:229], v[64:67]
	v_mfma_f32_16x16x32_bf16 v[108:111], v[168:171], v[184:187], v[108:111]
	v_mfma_f32_16x16x32_bf16 v[104:107], v[176:179], v[184:187], v[104:107]
	v_mfma_f32_16x16x32_bf16 v[92:95], v[168:171], v[192:195], v[92:95]
	v_mfma_f32_16x16x32_bf16 v[88:91], v[176:179], v[192:195], v[88:91]
	v_mfma_f32_16x16x32_bf16 v[76:79], v[168:171], v[222:225], v[76:79]
	v_mfma_f32_16x16x32_bf16 v[72:75], v[176:179], v[222:225], v[72:75]
	v_mfma_f32_16x16x32_bf16 v[68:71], v[168:171], v[230:233], v[68:71]
	v_mfma_f32_16x16x32_bf16 v[64:67], v[176:179], v[230:233], v[64:67]
	s_setprio 0
	s_barrier
	s_add_i32 s88, s88, s28
	s_mov_b32 m0, s88
	ds_read_b128 v[180:183], v141 offset:16384
	ds_read_b128 v[184:187], v141 offset:17408
	ds_read_b128 v[188:191], v141 offset:18432
	ds_read_b128 v[192:195], v141 offset:19456
	ds_read_b128 v[196:199], v141 offset:20480
	ds_read_b128 v[222:225], v141 offset:21504
	ds_read_b128 v[226:229], v141 offset:22528
	ds_read_b128 v[230:233], v141 offset:23552
	global_load_lds_dwordx4 v160, s[4:5]
	s_add_i32 m0, s88, 0x2000
	s_add_u32 s88, s4, 0x80000
	s_addc_u32 s89, s5, 0
	s_add_i32 s90, s90, s28
	global_load_lds_dwordx4 v128, s[4:5]
	s_mov_b32 m0, s90
	s_nop 0
	global_load_lds_dwordx4 v160, s[88:89]
	s_add_i32 m0, s90, 0x2000
	s_nop 0
	global_load_lds_dwordx4 v128, s[88:89]
	s_mov_b32 m0, s29
	s_nop 0
	global_load_lds_dwordx4 v132, s[52:53]
	s_mov_b32 m0, s45
	s_nop 0
	global_load_lds_dwordx4 v130, s[52:53]
	s_add_u32 s98, s52, 0x80
	s_addc_u32 s99, s53, 0
	s_waitcnt vmcnt(8)
	s_waitcnt lgkmcnt(0)
	s_barrier
	s_setprio 1
	s_waitcnt lgkmcnt(0)
	v_mfma_f32_16x16x32_bf16 v[60:63], v[142:145], v[180:183], v[60:63]
	v_mfma_f32_16x16x32_bf16 v[56:59], v[150:153], v[180:183], v[56:59]
	v_mfma_f32_16x16x32_bf16 v[52:55], v[142:145], v[188:191], v[52:55]
	v_mfma_f32_16x16x32_bf16 v[48:51], v[150:153], v[188:191], v[48:51]
	v_mfma_f32_16x16x32_bf16 v[36:39], v[142:145], v[196:199], v[36:39]
	v_mfma_f32_16x16x32_bf16 v[32:35], v[150:153], v[196:199], v[32:35]
	v_mfma_f32_16x16x32_bf16 v[20:23], v[142:145], v[226:229], v[20:23]
	v_mfma_f32_16x16x32_bf16 v[16:19], v[150:153], v[226:229], v[16:19]
	v_mfma_f32_16x16x32_bf16 v[60:63], v[146:149], v[184:187], v[60:63]
	v_mfma_f32_16x16x32_bf16 v[56:59], v[154:157], v[184:187], v[56:59]
	v_mfma_f32_16x16x32_bf16 v[52:55], v[146:149], v[192:195], v[52:55]
	v_mfma_f32_16x16x32_bf16 v[48:51], v[154:157], v[192:195], v[48:51]
	v_mfma_f32_16x16x32_bf16 v[36:39], v[146:149], v[222:225], v[36:39]
	v_mfma_f32_16x16x32_bf16 v[32:35], v[154:157], v[222:225], v[32:35]
	v_mfma_f32_16x16x32_bf16 v[20:23], v[146:149], v[230:233], v[20:23]
	v_mfma_f32_16x16x32_bf16 v[16:19], v[154:157], v[230:233], v[16:19]
	s_setprio 0
	s_setprio 1
	v_mfma_f32_16x16x32_bf16 v[44:47], v[164:167], v[180:183], v[44:47]
	v_mfma_f32_16x16x32_bf16 v[40:43], v[172:175], v[180:183], v[40:43]
	v_mfma_f32_16x16x32_bf16 v[28:31], v[164:167], v[188:191], v[28:31]
	v_mfma_f32_16x16x32_bf16 v[24:27], v[172:175], v[188:191], v[24:27]
	v_mfma_f32_16x16x32_bf16 v[12:15], v[164:167], v[196:199], v[12:15]
	v_mfma_f32_16x16x32_bf16 v[8:11], v[172:175], v[196:199], v[8:11]
	v_mfma_f32_16x16x32_bf16 v[4:7], v[164:167], v[226:229], v[4:7]
	v_mfma_f32_16x16x32_bf16 v[0:3], v[172:175], v[226:229], v[0:3]
	v_mfma_f32_16x16x32_bf16 v[44:47], v[168:171], v[184:187], v[44:47]
	v_mfma_f32_16x16x32_bf16 v[40:43], v[176:179], v[184:187], v[40:43]
	v_mfma_f32_16x16x32_bf16 v[28:31], v[168:171], v[192:195], v[28:31]
	v_mfma_f32_16x16x32_bf16 v[24:27], v[176:179], v[192:195], v[24:27]
	v_mfma_f32_16x16x32_bf16 v[12:15], v[168:171], v[222:225], v[12:15]
	v_mfma_f32_16x16x32_bf16 v[8:11], v[176:179], v[222:225], v[8:11]
	v_mfma_f32_16x16x32_bf16 v[4:7], v[168:171], v[230:233], v[4:7]
	v_mfma_f32_16x16x32_bf16 v[0:3], v[176:179], v[230:233], v[0:3]
	s_setprio 0
	s_barrier
; #define PG8_STAGE(bufoff, gbase, voff) do { _Pragma("unroll") for (int _i = 0; _i < 2; ++_i) \
;         __builtin_amdgcn_global_load_lds((const unsigned*)((const char*)(gbase) + (voff)[_i]), (PG8_LAS unsigned*)(lds + (bufoff) + ldsw + _i * 8192), 16, 0, 0); } while (0)
; #define PG8_LDA(dst, b, h) do { _Pragma("unroll") for (int m = 0; m < 4; ++m) _Pragma("unroll") for (int k = 0; k < 2; ++k) dst[m][k] = *(const PG8_LAS bf16x8*)(lds + PG8_SA(b, h) + aoff + m * 2048 + k * 1024); } while (0)
; #define PG8_LDB(dst, b, h) do { _Pragma("unroll") for (int n = 0; n < 2; ++n) _Pragma("unroll") for (int k = 0; k < 2; ++k) dst[n][k] = *(const PG8_LAS bf16x8*)(lds + PG8_SB(b, h) + boff + n * 2048 + k * 1024); } while (0)
; #define PG8_MMA(ai, bj, At, Bt) do { __builtin_amdgcn_s_setprio(1); _Pragma("unroll") for (int m = 0; m < 4; ++m) _Pragma("unroll") for (int n = 0; n < 2; ++n) _Pragma("unroll") for (int k = 0; k < 2; ++k) \
;         acc[ai][bj][m][n] = __builtin_amdgcn_mfma_f32_16x16x32_bf16(Bt[n][k], At[m][k], acc[ai][bj][m][n], 0, 0, 0); __builtin_amdgcn_s_setprio(0); } while (0)
; #define PG8_WAIT_V(n) asm volatile("s_waitcnt vmcnt(" #n ")" ::: "memory")
; #define PG8_WAIT_L(n) asm volatile("s_waitcnt lgkmcnt(" #n ")" ::: "memory")
; #define PG8_BAR __builtin_amdgcn_s_barrier()
; #define PG8_SCHED __builtin_amdgcn_sched_barrier(0)
; template <class Epi, class Sched, bool ALIGN_EPI = false, bool SP2 = false>
; __device__ __forceinline__ void gemm_phase(PG8_LAS unsigned char* lds, const Gemm g, const Sched& S, const Epi& E) {
;     ...
;             PG8_LDB(B0, 1, 0); PG8_LDB(B1, 1, 1); PG8_SCHED; PG8_LDA(At, 1, 0); PG8_STAGE(PG8_SA(0, 1), a2 + hstep, voffA);
;             PG8_WAIT_V(8); PG8_WAIT_L(0); PG8_BAR; PG8_MMA(0, 0, At, B0); PG8_MMA(0, 1, At, B1); PG8_BAR; PG8_SCHED;
;             PG8_LDA(At, 1, 1); PG8_STAGE(PG8_SB(1, 0), b3, voffB); PG8_STAGE(PG8_SB(1, 1), b3 + hstep, voffB); PG8_STAGE(PG8_SA(1, 0), a3, voffA);
;             PG8_WAIT_V(8); PG8_WAIT_L(0); PG8_BAR; PG8_MMA(1, 0, At, B0); PG8_MMA(1, 1, At, B1); PG8_BAR; PG8_SCHED;
	s_add_i32 s88, 0, 0x18000
	s_add_i32 s89, 0, 0x1c000
	ds_read_b128 v[142:145], v200 offset:32768
	ds_read_b128 v[146:149], v200 offset:33792
	ds_read_b128 v[150:153], v200 offset:34816
	ds_read_b128 v[154:157], v200 offset:35840
	ds_read_b128 v[164:167], v200 offset:49152
	ds_read_b128 v[168:171], v200 offset:50176
	ds_read_b128 v[172:175], v200 offset:51200
	ds_read_b128 v[176:179], v200 offset:52224
	s_add_u32 s52, s52, 0x80000
	s_addc_u32 s53, s53, 0
	s_mov_b32 m0, s56
	ds_read_b128 v[180:183], v141 offset:32768
	ds_read_b128 v[184:187], v141 offset:33792
	ds_read_b128 v[188:191], v141 offset:34816
	ds_read_b128 v[192:195], v141 offset:35840
	ds_read_b128 v[196:199], v141 offset:36864
	ds_read_b128 v[222:225], v141 offset:37888
	ds_read_b128 v[226:229], v141 offset:38912
	ds_read_b128 v[230:233], v141 offset:39936
	global_load_lds_dwordx4 v132, s[52:53]
	s_mov_b32 m0, s57
	s_nop 0
	global_load_lds_dwordx4 v130, s[52:53]
	s_waitcnt vmcnt(8)
	s_waitcnt lgkmcnt(0)
	s_barrier
	s_setprio 1
	s_waitcnt lgkmcnt(0)
	v_mfma_f32_16x16x32_bf16 v[124:127], v[142:145], v[180:183], v[124:127]
	v_mfma_f32_16x16x32_bf16 v[120:123], v[150:153], v[180:183], v[120:123]
	v_mfma_f32_16x16x32_bf16 v[116:119], v[142:145], v[188:191], v[116:119]
	v_mfma_f32_16x16x32_bf16 v[112:115], v[150:153], v[188:191], v[112:115]
	v_mfma_f32_16x16x32_bf16 v[100:103], v[142:145], v[196:199], v[100:103]
	v_mfma_f32_16x16x32_bf16 v[96:99], v[150:153], v[196:199], v[96:99]
	v_mfma_f32_16x16x32_bf16 v[84:87], v[142:145], v[226:229], v[84:87]
	v_mfma_f32_16x16x32_bf16 v[80:83], v[150:153], v[226:229], v[80:83]
	v_mfma_f32_16x16x32_bf16 v[124:127], v[146:149], v[184:187], v[124:127]
	v_mfma_f32_16x16x32_bf16 v[120:123], v[154:157], v[184:187], v[120:123]
	v_mfma_f32_16x16x32_bf16 v[116:119], v[146:149], v[192:195], v[116:119]
	v_mfma_f32_16x16x32_bf16 v[112:115], v[154:157], v[192:195], v[112:115]
	v_mfma_f32_16x16x32_bf16 v[100:103], v[146:149], v[222:225], v[100:103]
	v_mfma_f32_16x16x32_bf16 v[96:99], v[154:157], v[222:225], v[96:99]
	v_mfma_f32_16x16x32_bf16 v[84:87], v[146:149], v[230:233], v[84:87]
	v_mfma_f32_16x16x32_bf16 v[80:83], v[154:157], v[230:233], v[80:83]
	s_setprio 0
	s_setprio 1
	v_mfma_f32_16x16x32_bf16 v[108:111], v[164:167], v[180:183], v[108:111]
	v_mfma_f32_16x16x32_bf16 v[104:107], v[172:175], v[180:183], v[104:107]
	v_mfma_f32_16x16x32_bf16 v[92:95], v[164:167], v[188:191], v[92:95]
	v_mfma_f32_16x16x32_bf16 v[88:91], v[172:175], v[188:191], v[88:91]
	v_mfma_f32_16x16x32_bf16 v[76:79], v[164:167], v[196:199], v[76:79]
	v_mfma_f32_16x16x32_bf16 v[72:75], v[172:175], v[196:199], v[72:75]
	v_mfma_f32_16x16x32_bf16 v[68:71], v[164:167], v[226:229], v[68:71]
	v_mfma_f32_16x16x32_bf16 v[64:67], v[172:175], v[226:229], v[64:67]
	v_mfma_f32_16x16x32_bf16 v[108:111], v[168:171], v[184:187], v[108:111]
	v_mfma_f32_16x16x32_bf16 v[104:107], v[176:179], v[184:187], v[104:107]
	v_mfma_f32_16x16x32_bf16 v[92:95], v[168:171], v[192:195], v[92:95]
	v_mfma_f32_16x16x32_bf16 v[88:91], v[176:179], v[192:195], v[88:91]
	v_mfma_f32_16x16x32_bf16 v[76:79], v[168:171], v[222:225], v[76:79]
	v_mfma_f32_16x16x32_bf16 v[72:75], v[176:179], v[222:225], v[72:75]
	v_mfma_f32_16x16x32_bf16 v[68:71], v[168:171], v[230:233], v[68:71]
	v_mfma_f32_16x16x32_bf16 v[64:67], v[176:179], v[230:233], v[64:67]
	s_setprio 0
	s_barrier
	s_add_i32 s52, s88, s28
	s_mov_b32 m0, s52
	ds_read_b128 v[180:183], v141 offset:49152
	ds_read_b128 v[184:187], v141 offset:50176
	ds_read_b128 v[188:191], v141 offset:51200
	ds_read_b128 v[192:195], v141 offset:52224
	ds_read_b128 v[196:199], v141 offset:53248
	ds_read_b128 v[222:225], v141 offset:54272
	ds_read_b128 v[226:229], v141 offset:55296
	ds_read_b128 v[230:233], v141 offset:56320
	s_add_u32 s4, s4, 0x80
	s_addc_u32 s5, s5, 0
	global_load_lds_dwordx4 v160, s[4:5]
	s_add_i32 m0, s52, 0x2000
	s_add_i32 s52, s89, s28
	global_load_lds_dwordx4 v128, s[4:5]
	s_add_u32 s4, s4, 0x80000
	s_addc_u32 s5, s5, 0
	s_mov_b32 m0, s52
	s_nop 0
	global_load_lds_dwordx4 v160, s[4:5]
	s_add_i32 m0, s52, 0x2000
	s_nop 0
	global_load_lds_dwordx4 v128, s[4:5]
	s_mov_b32 m0, s24
	s_nop 0
	global_load_lds_dwordx4 v132, s[98:99]
	s_mov_b32 m0, s59
	s_nop 0
	global_load_lds_dwordx4 v130, s[98:99]
	s_waitcnt vmcnt(8)
	s_waitcnt lgkmcnt(0)
	s_barrier
	s_setprio 1
	s_waitcnt lgkmcnt(0)
	v_mfma_f32_16x16x32_bf16 v[60:63], v[142:145], v[180:183], v[60:63]
	v_mfma_f32_16x16x32_bf16 v[56:59], v[150:153], v[180:183], v[56:59]
	v_mfma_f32_16x16x32_bf16 v[52:55], v[142:145], v[188:191], v[52:55]
	v_mfma_f32_16x16x32_bf16 v[48:51], v[150:153], v[188:191], v[48:51]
	v_mfma_f32_16x16x32_bf16 v[36:39], v[142:145], v[196:199], v[36:39]
	v_mfma_f32_16x16x32_bf16 v[32:35], v[150:153], v[196:199], v[32:35]
	v_mfma_f32_16x16x32_bf16 v[20:23], v[142:145], v[226:229], v[20:23]
	v_mfma_f32_16x16x32_bf16 v[16:19], v[150:153], v[226:229], v[16:19]
	v_mfma_f32_16x16x32_bf16 v[60:63], v[146:149], v[184:187], v[60:63]
	v_mfma_f32_16x16x32_bf16 v[56:59], v[154:157], v[184:187], v[56:59]
	v_mfma_f32_16x16x32_bf16 v[52:55], v[146:149], v[192:195], v[52:55]
	v_mfma_f32_16x16x32_bf16 v[48:51], v[154:157], v[192:195], v[48:51]
	v_mfma_f32_16x16x32_bf16 v[36:39], v[146:149], v[222:225], v[36:39]
	v_mfma_f32_16x16x32_bf16 v[32:35], v[154:157], v[222:225], v[32:35]
	v_mfma_f32_16x16x32_bf16 v[20:23], v[146:149], v[230:233], v[20:23]
	v_mfma_f32_16x16x32_bf16 v[16:19], v[154:157], v[230:233], v[16:19]
	s_setprio 0
	s_setprio 1
	v_mfma_f32_16x16x32_bf16 v[44:47], v[164:167], v[180:183], v[44:47]
	v_mfma_f32_16x16x32_bf16 v[40:43], v[172:175], v[180:183], v[40:43]
	v_mfma_f32_16x16x32_bf16 v[28:31], v[164:167], v[188:191], v[28:31]
	v_mfma_f32_16x16x32_bf16 v[24:27], v[172:175], v[188:191], v[24:27]
	v_mfma_f32_16x16x32_bf16 v[12:15], v[164:167], v[196:199], v[12:15]
	v_mfma_f32_16x16x32_bf16 v[8:11], v[172:175], v[196:199], v[8:11]
	v_mfma_f32_16x16x32_bf16 v[4:7], v[164:167], v[226:229], v[4:7]
	v_mfma_f32_16x16x32_bf16 v[0:3], v[172:175], v[226:229], v[0:3]
	v_mfma_f32_16x16x32_bf16 v[44:47], v[168:171], v[184:187], v[44:47]
	v_mfma_f32_16x16x32_bf16 v[40:43], v[176:179], v[184:187], v[40:43]
	v_mfma_f32_16x16x32_bf16 v[28:31], v[168:171], v[192:195], v[28:31]
	v_mfma_f32_16x16x32_bf16 v[24:27], v[176:179], v[192:195], v[24:27]
	v_mfma_f32_16x16x32_bf16 v[12:15], v[168:171], v[222:225], v[12:15]
	v_mfma_f32_16x16x32_bf16 v[8:11], v[176:179], v[222:225], v[8:11]
	v_mfma_f32_16x16x32_bf16 v[4:7], v[168:171], v[230:233], v[4:7]
	v_mfma_f32_16x16x32_bf16 v[0:3], v[176:179], v[230:233], v[0:3]
	s_setprio 0
	s_barrier
	s_add_i32 s87, s87, 2
	s_add_u32 s80, s80, 0x100
	s_addc_u32 s81, s81, 0
	s_add_u32 s85, s85, 0x100
	s_addc_u32 s86, s86, 0
	s_cmp_gt_u32 s87, 29
	s_cbranch_scc0 .LBB0_25
	s_and_b64 vcc, exec, s[42:43]
	s_cbranch_vccz .LBB0_28
	s_barrier

; #define PG8_STAGE(bufoff, gbase, voff) do { _Pragma("unroll") for (int _i = 0; _i < 2; ++_i) \
;         __builtin_amdgcn_global_load_lds((const unsigned*)((const char*)(gbase) + (voff)[_i]), (PG8_LAS unsigned*)(lds + (bufoff) + ldsw + _i * 8192), 16, 0, 0); } while (0)
; #define PG8_LDA(dst, b, h) do { _Pragma("unroll") for (int m = 0; m < 4; ++m) _Pragma("unroll") for (int k = 0; k < 2; ++k) dst[m][k] = *(const PG8_LAS bf16x8*)(lds + PG8_SA(b, h) + aoff + m * 2048 + k * 1024); } while (0)
; #define PG8_LDB(dst, b, h) do { _Pragma("unroll") for (int n = 0; n < 2; ++n) _Pragma("unroll") for (int k = 0; k < 2; ++k) dst[n][k] = *(const PG8_LAS bf16x8*)(lds + PG8_SB(b, h) + boff + n * 2048 + k * 1024); } while (0)
; #define PG8_MMA(ai, bj, At, Bt) do { __builtin_amdgcn_s_setprio(1); _Pragma("unroll") for (int m = 0; m < 4; ++m) _Pragma("unroll") for (int n = 0; n < 2; ++n) _Pragma("unroll") for (int k = 0; k < 2; ++k) \
;         acc[ai][bj][m][n] = __builtin_amdgcn_mfma_f32_16x16x32_bf16(Bt[n][k], At[m][k], acc[ai][bj][m][n], 0, 0, 0); __builtin_amdgcn_s_setprio(0); } while (0)
; #define PG8_WAIT_V(n) asm volatile("s_waitcnt vmcnt(" #n ")" ::: "memory")
; #define PG8_WAIT_L(n) asm volatile("s_waitcnt lgkmcnt(" #n ")" ::: "memory")
; template <class Epi, class Sched, bool ALIGN_EPI = false, bool SP2 = false>
; __device__ __forceinline__ void gemm_phase(PG8_LAS unsigned char* lds, const Gemm g, const Sched& S, const Epi& E) {
;     ...
;             const bool last = (t == nt - 2);
;             const char* a1 = cA + (size_t)(t + 1) * kstep;
;             const char* a2 = last ? nA : cA + (size_t)(t + 2) * kstep; const char* b2 = last ? nB : cB + (size_t)(t + 2) * kstep;
;             const char* a3 = a2 + kstep; const char* b3 = b2 + kstep;
;             if (last && has_next) S.a_ready(nxt);
;             if constexpr (SP2) {
;             PG8_LDB(B0, 0, 0); PG8_LDB(B1, 0, 1); PG8_SCHED; PG8_LDA(At, 0, 0); PG8_STAGE(PG8_SA(1, 1), a1 + hstep, voffA);
;             PG8_WAIT_V(8); PG8_WAIT_L(0); PG8_BAR; PG8_MMA(0, 0, At, B0); PG8_MMA(0, 1, At, B1); PG8_BAR; PG8_SCHED;
;     ...
;         for (int a = 0; a < 2; ++a)
; #pragma unroll
;             for (int b = 0; b < 2; ++b)
; #pragma unroll
;                 for (int m = 0; m < 4; ++m)
; #pragma unroll
;                     for (int n = 0; n < 2; ++n) acc[a][b][m][n] = (f32x4){0.f, 0.f, 0.f, 0.f};
.LBB0_51:
	s_add_u32 s81, s4, 0x100
	v_mov_b32_e32 v0, 0
	s_addc_u32 s82, s5, 0
	s_mov_b32 s83, -2
	v_add_u32_e32 v200, 0x10000, v139
	v_mov_b32_e32 v1, v0
	v_mov_b32_e32 v2, v0
	v_mov_b32_e32 v3, v0
	v_mov_b32_e32 v4, v0
	v_mov_b32_e32 v5, v0
	v_mov_b32_e32 v6, v0
	v_mov_b32_e32 v7, v0
	v_mov_b32_e32 v8, v0
	v_mov_b32_e32 v9, v0
	v_mov_b32_e32 v10, v0
	v_mov_b32_e32 v11, v0
	v_mov_b32_e32 v12, v0
	v_mov_b32_e32 v13, v0
	v_mov_b32_e32 v14, v0
	v_mov_b32_e32 v15, v0
	v_mov_b32_e32 v24, v0
	v_mov_b32_e32 v25, v0
	v_mov_b32_e32 v26, v0
	v_mov_b32_e32 v27, v0
	v_mov_b32_e32 v28, v0
	v_mov_b32_e32 v29, v0
	v_mov_b32_e32 v30, v0
	v_mov_b32_e32 v31, v0
	v_mov_b32_e32 v40, v0
	v_mov_b32_e32 v41, v0
	v_mov_b32_e32 v42, v0
	v_mov_b32_e32 v43, v0
	v_mov_b32_e32 v44, v0
	v_mov_b32_e32 v45, v0
	v_mov_b32_e32 v46, v0
	v_mov_b32_e32 v47, v0
	v_mov_b32_e32 v16, v0
	v_mov_b32_e32 v17, v0
	v_mov_b32_e32 v18, v0
	v_mov_b32_e32 v19, v0
	v_mov_b32_e32 v20, v0
	v_mov_b32_e32 v21, v0
	v_mov_b32_e32 v22, v0
	v_mov_b32_e32 v23, v0
	v_mov_b32_e32 v32, v0
	v_mov_b32_e32 v33, v0
	v_mov_b32_e32 v34, v0
	v_mov_b32_e32 v35, v0
	v_mov_b32_e32 v36, v0
	v_mov_b32_e32 v37, v0
	v_mov_b32_e32 v38, v0
	v_mov_b32_e32 v39, v0
	v_mov_b32_e32 v48, v0
	v_mov_b32_e32 v49, v0
	v_mov_b32_e32 v50, v0
	v_mov_b32_e32 v51, v0
	v_mov_b32_e32 v52, v0
	v_mov_b32_e32 v53, v0
	v_mov_b32_e32 v54, v0
	v_mov_b32_e32 v55, v0
	v_mov_b32_e32 v56, v0
	v_mov_b32_e32 v57, v0
	v_mov_b32_e32 v58, v0
	v_mov_b32_e32 v59, v0
	v_mov_b32_e32 v60, v0
	v_mov_b32_e32 v61, v0
	v_mov_b32_e32 v62, v0
	v_mov_b32_e32 v63, v0
	v_mov_b32_e32 v64, v0
	v_mov_b32_e32 v65, v0
	v_mov_b32_e32 v66, v0
	v_mov_b32_e32 v67, v0
	v_mov_b32_e32 v68, v0
	v_mov_b32_e32 v69, v0
	v_mov_b32_e32 v70, v0
	v_mov_b32_e32 v71, v0
	v_mov_b32_e32 v72, v0
	v_mov_b32_e32 v73, v0
	v_mov_b32_e32 v74, v0
	v_mov_b32_e32 v75, v0
	v_mov_b32_e32 v76, v0
	v_mov_b32_e32 v77, v0
	v_mov_b32_e32 v78, v0
	v_mov_b32_e32 v79, v0
	v_mov_b32_e32 v88, v0
	v_mov_b32_e32 v89, v0
	v_mov_b32_e32 v90, v0
	v_mov_b32_e32 v91, v0
	v_mov_b32_e32 v92, v0
	v_mov_b32_e32 v93, v0
	v_mov_b32_e32 v94, v0
	v_mov_b32_e32 v95, v0
	v_mov_b32_e32 v104, v0
	v_mov_b32_e32 v105, v0
	v_mov_b32_e32 v106, v0
	v_mov_b32_e32 v107, v0
	v_mov_b32_e32 v108, v0
	v_mov_b32_e32 v109, v0
	v_mov_b32_e32 v110, v0
	v_mov_b32_e32 v111, v0
	v_mov_b32_e32 v80, v0
	v_mov_b32_e32 v81, v0
	v_mov_b32_e32 v82, v0
	v_mov_b32_e32 v83, v0
	v_mov_b32_e32 v84, v0
	v_mov_b32_e32 v85, v0
	v_mov_b32_e32 v86, v0
	v_mov_b32_e32 v87, v0
	v_mov_b32_e32 v96, v0
	v_mov_b32_e32 v97, v0
	v_mov_b32_e32 v98, v0
	v_mov_b32_e32 v99, v0
	v_mov_b32_e32 v100, v0
	v_mov_b32_e32 v101, v0
	v_mov_b32_e32 v102, v0
	v_mov_b32_e32 v103, v0
	v_mov_b32_e32 v112, v0
	v_mov_b32_e32 v113, v0
	v_mov_b32_e32 v114, v0
	v_mov_b32_e32 v115, v0
	v_mov_b32_e32 v116, v0
	v_mov_b32_e32 v117, v0
	v_mov_b32_e32 v118, v0
	v_mov_b32_e32 v119, v0
	v_mov_b32_e32 v120, v0
	v_mov_b32_e32 v121, v0
	v_mov_b32_e32 v122, v0
	v_mov_b32_e32 v123, v0
	v_mov_b32_e32 v124, v0
	v_mov_b32_e32 v125, v0
	v_mov_b32_e32 v126, v0
	v_mov_b32_e32 v127, v0
.LBB0_52:
	s_add_i32 s84, 0, 0x10000
	s_add_i32 s85, 0, 0x14000
	ds_read_b128 v[142:145], v200
	ds_read_b128 v[146:149], v200 offset:1024
	ds_read_b128 v[150:153], v200 offset:2048
	ds_read_b128 v[154:157], v200 offset:3072
	ds_read_b128 v[164:167], v200 offset:16384
	ds_read_b128 v[168:171], v200 offset:17408
	ds_read_b128 v[172:175], v200 offset:18432
	ds_read_b128 v[176:179], v200 offset:19456
	s_add_i32 m0, s28, 0xc000
	ds_read_b128 v[180:183], v141
	ds_read_b128 v[184:187], v141 offset:1024
	ds_read_b128 v[188:191], v141 offset:2048
	ds_read_b128 v[192:195], v141 offset:3072
	ds_read_b128 v[196:199], v141 offset:4096
	ds_read_b128 v[222:225], v141 offset:5120
	ds_read_b128 v[226:229], v141 offset:6144
	ds_read_b128 v[230:233], v141 offset:7168
	global_load_lds_dwordx4 v134, s[72:73]
	s_add_i32 m0, s28, 0xe000
	s_nop 0
	global_load_lds_dwordx4 v136, s[72:73]
	s_add_u32 s4, s72, 0x100
	s_addc_u32 s5, s73, 0
	s_cmpk_eq_i32 s83, 0x54
	s_cselect_b32 s57, s45, s5
	s_cselect_b32 s56, s44, s4
	s_cselect_b32 s53, s55, s82
	s_cselect_b32 s52, s54, s81
	s_waitcnt vmcnt(8)
	s_waitcnt lgkmcnt(0)
	s_barrier
	s_setprio 1
	s_waitcnt lgkmcnt(0)
	v_mfma_f32_16x16x32_bf16 v[124:127], v[142:145], v[180:183], v[124:127]
	v_mfma_f32_16x16x32_bf16 v[120:123], v[150:153], v[180:183], v[120:123]
	v_mfma_f32_16x16x32_bf16 v[116:119], v[142:145], v[188:191], v[116:119]
	v_mfma_f32_16x16x32_bf16 v[112:115], v[150:153], v[188:191], v[112:115]
	v_mfma_f32_16x16x32_bf16 v[100:103], v[142:145], v[196:199], v[100:103]
	v_mfma_f32_16x16x32_bf16 v[96:99], v[150:153], v[196:199], v[96:99]
	v_mfma_f32_16x16x32_bf16 v[84:87], v[142:145], v[226:229], v[84:87]
	v_mfma_f32_16x16x32_bf16 v[80:83], v[150:153], v[226:229], v[80:83]
	v_mfma_f32_16x16x32_bf16 v[124:127], v[146:149], v[184:187], v[124:127]
	v_mfma_f32_16x16x32_bf16 v[120:123], v[154:157], v[184:187], v[120:123]
	v_mfma_f32_16x16x32_bf16 v[116:119], v[146:149], v[192:195], v[116:119]
	v_mfma_f32_16x16x32_bf16 v[112:115], v[154:157], v[192:195], v[112:115]
	v_mfma_f32_16x16x32_bf16 v[100:103], v[146:149], v[222:225], v[100:103]
	v_mfma_f32_16x16x32_bf16 v[96:99], v[154:157], v[222:225], v[96:99]
	v_mfma_f32_16x16x32_bf16 v[84:87], v[146:149], v[230:233], v[84:87]
	v_mfma_f32_16x16x32_bf16 v[80:83], v[154:157], v[230:233], v[80:83]
	s_setprio 0
	s_setprio 1
	v_mfma_f32_16x16x32_bf16 v[108:111], v[164:167], v[180:183], v[108:111]
	v_mfma_f32_16x16x32_bf16 v[104:107], v[172:175], v[180:183], v[104:107]
	v_mfma_f32_16x16x32_bf16 v[92:95], v[164:167], v[188:191], v[92:95]
	v_mfma_f32_16x16x32_bf16 v[88:91], v[172:175], v[188:191], v[88:91]
	v_mfma_f32_16x16x32_bf16 v[76:79], v[164:167], v[196:199], v[76:79]
	v_mfma_f32_16x16x32_bf16 v[72:75], v[172:175], v[196:199], v[72:75]
	v_mfma_f32_16x16x32_bf16 v[68:71], v[164:167], v[226:229], v[68:71]
	v_mfma_f32_16x16x32_bf16 v[64:67], v[172:175], v[226:229], v[64:67]
	v_mfma_f32_16x16x32_bf16 v[108:111], v[168:171], v[184:187], v[108:111]
	v_mfma_f32_16x16x32_bf16 v[104:107], v[176:179], v[184:187], v[104:107]
	v_mfma_f32_16x16x32_bf16 v[92:95], v[168:171], v[192:195], v[92:95]
	v_mfma_f32_16x16x32_bf16 v[88:91], v[176:179], v[192:195], v[88:91]
	v_mfma_f32_16x16x32_bf16 v[76:79], v[168:171], v[222:225], v[76:79]
	v_mfma_f32_16x16x32_bf16 v[72:75], v[176:179], v[222:225], v[72:75]
	v_mfma_f32_16x16x32_bf16 v[68:71], v[168:171], v[230:233], v[68:71]
	v_mfma_f32_16x16x32_bf16 v[64:67], v[176:179], v[230:233], v[64:67]
	s_setprio 0
	s_barrier
; #define PG8_STAGE(bufoff, gbase, voff) do { _Pragma("unroll") for (int _i = 0; _i < 2; ++_i) \
;         __builtin_amdgcn_global_load_lds((const unsigned*)((const char*)(gbase) + (voff)[_i]), (PG8_LAS unsigned*)(lds + (bufoff) + ldsw + _i * 8192), 16, 0, 0); } while (0)
; #define PG8_LDA(dst, b, h) do { _Pragma("unroll") for (int m = 0; m < 4; ++m) _Pragma("unroll") for (int k = 0; k < 2; ++k) dst[m][k] = *(const PG8_LAS bf16x8*)(lds + PG8_SA(b, h) + aoff + m * 2048 + k * 1024); } while (0)
; #define PG8_LDB(dst, b, h) do { _Pragma("unroll") for (int n = 0; n < 2; ++n) _Pragma("unroll") for (int k = 0; k < 2; ++k) dst[n][k] = *(const PG8_LAS bf16x8*)(lds + PG8_SB(b, h) + boff + n * 2048 + k * 1024); } while (0)
; #define PG8_MMA(ai, bj, At, Bt) do { __builtin_amdgcn_s_setprio(1); _Pragma("unroll") for (int m = 0; m < 4; ++m) _Pragma("unroll") for (int n = 0; n < 2; ++n) _Pragma("unroll") for (int k = 0; k < 2; ++k) \
;         acc[ai][bj][m][n] = __builtin_amdgcn_mfma_f32_16x16x32_bf16(Bt[n][k], At[m][k], acc[ai][bj][m][n], 0, 0, 0); __builtin_amdgcn_s_setprio(0); } while (0)
; #define PG8_WAIT_V(n) asm volatile("s_waitcnt vmcnt(" #n ")" ::: "memory")
; #define PG8_WAIT_L(n) asm volatile("s_waitcnt lgkmcnt(" #n ")" ::: "memory")
; #define PG8_BAR __builtin_amdgcn_s_barrier()
; #define PG8_SCHED __builtin_amdgcn_sched_barrier(0)
; template <class Epi, class Sched, bool ALIGN_EPI = false, bool SP2 = false>
; __device__ __forceinline__ void gemm_phase(PG8_LAS unsigned char* lds, const Gemm g, const Sched& S, const Epi& E) {
;     ...
;             PG8_LDA(At, 0, 1); PG8_STAGE(PG8_SB(0, 0), b2, voffB); PG8_STAGE(PG8_SB(0, 1), b2 + hstep, voffB); PG8_STAGE(PG8_SA(0, 0), a2, voffA);
;             PG8_WAIT_V(8); PG8_WAIT_L(0); PG8_BAR; PG8_MMA(1, 0, At, B0); PG8_MMA(1, 1, At, B1); PG8_BAR; PG8_SCHED;
;             PG8_LDB(B0, 1, 0); PG8_LDB(B1, 1, 1); PG8_SCHED; PG8_LDA(At, 1, 0); PG8_STAGE(PG8_SA(0, 1), a2 + hstep, voffA);
;             PG8_WAIT_V(8); PG8_WAIT_L(0); PG8_BAR; PG8_MMA(0, 0, At, B0); PG8_MMA(0, 1, At, B1); PG8_BAR; PG8_SCHED;
	s_add_i32 s72, s84, s24
	s_mov_b32 m0, s72
	ds_read_b128 v[180:183], v141 offset:16384
	ds_read_b128 v[184:187], v141 offset:17408
	ds_read_b128 v[188:191], v141 offset:18432
	ds_read_b128 v[192:195], v141 offset:19456
	ds_read_b128 v[196:199], v141 offset:20480
	ds_read_b128 v[222:225], v141 offset:21504
	ds_read_b128 v[226:229], v141 offset:22528
	ds_read_b128 v[230:233], v141 offset:23552
	global_load_lds_dwordx4 v160, s[52:53]
	s_add_i32 m0, s72, 0x2000
	s_add_u32 s72, s52, 0x160000
	s_addc_u32 s73, s53, 0
	s_add_i32 s84, s85, s24
	global_load_lds_dwordx4 v128, s[52:53]
	s_mov_b32 m0, s84
	s_nop 0
	global_load_lds_dwordx4 v160, s[72:73]
	s_add_i32 m0, s84, 0x2000
	s_nop 0
	global_load_lds_dwordx4 v128, s[72:73]
	s_mov_b32 m0, s28
	s_nop 0
	global_load_lds_dwordx4 v132, s[56:57]
	s_mov_b32 m0, s29
	s_nop 0
	global_load_lds_dwordx4 v130, s[56:57]
	s_add_u32 s98, s56, 0x80
	s_addc_u32 s99, s57, 0
	s_waitcnt vmcnt(8)
	s_waitcnt lgkmcnt(0)
	s_barrier
	s_setprio 1
	s_waitcnt lgkmcnt(0)
	v_mfma_f32_16x16x32_bf16 v[60:63], v[142:145], v[180:183], v[60:63]
	v_mfma_f32_16x16x32_bf16 v[56:59], v[150:153], v[180:183], v[56:59]
	v_mfma_f32_16x16x32_bf16 v[52:55], v[142:145], v[188:191], v[52:55]
	v_mfma_f32_16x16x32_bf16 v[48:51], v[150:153], v[188:191], v[48:51]
	v_mfma_f32_16x16x32_bf16 v[36:39], v[142:145], v[196:199], v[36:39]
	v_mfma_f32_16x16x32_bf16 v[32:35], v[150:153], v[196:199], v[32:35]
	v_mfma_f32_16x16x32_bf16 v[20:23], v[142:145], v[226:229], v[20:23]
	v_mfma_f32_16x16x32_bf16 v[16:19], v[150:153], v[226:229], v[16:19]
	v_mfma_f32_16x16x32_bf16 v[60:63], v[146:149], v[184:187], v[60:63]
	v_mfma_f32_16x16x32_bf16 v[56:59], v[154:157], v[184:187], v[56:59]
	v_mfma_f32_16x16x32_bf16 v[52:55], v[146:149], v[192:195], v[52:55]
	v_mfma_f32_16x16x32_bf16 v[48:51], v[154:157], v[192:195], v[48:51]
	v_mfma_f32_16x16x32_bf16 v[36:39], v[146:149], v[222:225], v[36:39]
	v_mfma_f32_16x16x32_bf16 v[32:35], v[154:157], v[222:225], v[32:35]
	v_mfma_f32_16x16x32_bf16 v[20:23], v[146:149], v[230:233], v[20:23]
	v_mfma_f32_16x16x32_bf16 v[16:19], v[154:157], v[230:233], v[16:19]
	s_setprio 0
	s_setprio 1
	v_mfma_f32_16x16x32_bf16 v[44:47], v[164:167], v[180:183], v[44:47]
	v_mfma_f32_16x16x32_bf16 v[40:43], v[172:175], v[180:183], v[40:43]
	v_mfma_f32_16x16x32_bf16 v[28:31], v[164:167], v[188:191], v[28:31]
	v_mfma_f32_16x16x32_bf16 v[24:27], v[172:175], v[188:191], v[24:27]
	v_mfma_f32_16x16x32_bf16 v[12:15], v[164:167], v[196:199], v[12:15]
	v_mfma_f32_16x16x32_bf16 v[8:11], v[172:175], v[196:199], v[8:11]
	v_mfma_f32_16x16x32_bf16 v[4:7], v[164:167], v[226:229], v[4:7]
	v_mfma_f32_16x16x32_bf16 v[0:3], v[172:175], v[226:229], v[0:3]
	v_mfma_f32_16x16x32_bf16 v[44:47], v[168:171], v[184:187], v[44:47]
	v_mfma_f32_16x16x32_bf16 v[40:43], v[176:179], v[184:187], v[40:43]
	v_mfma_f32_16x16x32_bf16 v[28:31], v[168:171], v[192:195], v[28:31]
	v_mfma_f32_16x16x32_bf16 v[24:27], v[176:179], v[192:195], v[24:27]
	v_mfma_f32_16x16x32_bf16 v[12:15], v[168:171], v[222:225], v[12:15]
	v_mfma_f32_16x16x32_bf16 v[8:11], v[176:179], v[222:225], v[8:11]
	v_mfma_f32_16x16x32_bf16 v[4:7], v[168:171], v[230:233], v[4:7]
	v_mfma_f32_16x16x32_bf16 v[0:3], v[176:179], v[230:233], v[0:3]
	s_setprio 0
	s_barrier
	s_add_i32 s72, 0, 0x18000
	s_add_i32 s73, 0, 0x1c000
	ds_read_b128 v[142:145], v200 offset:32768
	ds_read_b128 v[146:149], v200 offset:33792
	ds_read_b128 v[150:153], v200 offset:34816
	ds_read_b128 v[154:157], v200 offset:35840
	ds_read_b128 v[164:167], v200 offset:49152
	ds_read_b128 v[168:171], v200 offset:50176
	ds_read_b128 v[172:175], v200 offset:51200
	ds_read_b128 v[176:179], v200 offset:52224
	s_add_u32 s56, s56, 0x160000
	s_addc_u32 s57, s57, 0
	s_mov_b32 m0, s59
	ds_read_b128 v[180:183], v141 offset:32768
	ds_read_b128 v[184:187], v141 offset:33792
	ds_read_b128 v[188:191], v141 offset:34816
	ds_read_b128 v[192:195], v141 offset:35840
	ds_read_b128 v[196:199], v141 offset:36864
	ds_read_b128 v[222:225], v141 offset:37888
	ds_read_b128 v[226:229], v141 offset:38912
	ds_read_b128 v[230:233], v141 offset:39936
	global_load_lds_dwordx4 v132, s[56:57]
	s_mov_b32 m0, s63
	s_nop 0
	global_load_lds_dwordx4 v130, s[56:57]
	s_waitcnt vmcnt(8)
	s_waitcnt lgkmcnt(0)
	s_barrier
; #define PG8_STAGE(bufoff, gbase, voff) do { _Pragma("unroll") for (int _i = 0; _i < 2; ++_i) \
;         __builtin_amdgcn_global_load_lds((const unsigned*)((const char*)(gbase) + (voff)[_i]), (PG8_LAS unsigned*)(lds + (bufoff) + ldsw + _i * 8192), 16, 0, 0); } while (0)
; #define PG8_LDA(dst, b, h) do { _Pragma("unroll") for (int m = 0; m < 4; ++m) _Pragma("unroll") for (int k = 0; k < 2; ++k) dst[m][k] = *(const PG8_LAS bf16x8*)(lds + PG8_SA(b, h) + aoff + m * 2048 + k * 1024); } while (0)
; #define PG8_MMA(ai, bj, At, Bt) do { __builtin_amdgcn_s_setprio(1); _Pragma("unroll") for (int m = 0; m < 4; ++m) _Pragma("unroll") for (int n = 0; n < 2; ++n) _Pragma("unroll") for (int k = 0; k < 2; ++k) \
;         acc[ai][bj][m][n] = __builtin_amdgcn_mfma_f32_16x16x32_bf16(Bt[n][k], At[m][k], acc[ai][bj][m][n], 0, 0, 0); __builtin_amdgcn_s_setprio(0); } while (0)
; #define PG8_WAIT_V(n) asm volatile("s_waitcnt vmcnt(" #n ")" ::: "memory")
; #define PG8_WAIT_L(n) asm volatile("s_waitcnt lgkmcnt(" #n ")" ::: "memory")
; #define PG8_BAR __builtin_amdgcn_s_barrier()
; #define PG8_SCHED __builtin_amdgcn_sched_barrier(0)
; template <class Epi, class Sched, bool ALIGN_EPI = false, bool SP2 = false>
; __device__ __forceinline__ void gemm_phase(PG8_LAS unsigned char* lds, const Gemm g, const Sched& S, const Epi& E) {
;     ...
;             PG8_WAIT_V(8); PG8_WAIT_L(0); PG8_BAR; PG8_MMA(0, 0, At, B0); PG8_MMA(0, 1, At, B1); PG8_BAR; PG8_SCHED;
;             PG8_LDA(At, 1, 1); PG8_STAGE(PG8_SB(1, 0), b3, voffB); PG8_STAGE(PG8_SB(1, 1), b3 + hstep, voffB); PG8_STAGE(PG8_SA(1, 0), a3, voffA);
;             PG8_WAIT_V(8); PG8_WAIT_L(0); PG8_BAR; PG8_MMA(1, 0, At, B0); PG8_MMA(1, 1, At, B1); PG8_BAR; PG8_SCHED;
	s_setprio 1
	s_waitcnt lgkmcnt(0)
	v_mfma_f32_16x16x32_bf16 v[124:127], v[142:145], v[180:183], v[124:127]
	v_mfma_f32_16x16x32_bf16 v[120:123], v[150:153], v[180:183], v[120:123]
	v_mfma_f32_16x16x32_bf16 v[116:119], v[142:145], v[188:191], v[116:119]
	v_mfma_f32_16x16x32_bf16 v[112:115], v[150:153], v[188:191], v[112:115]
	v_mfma_f32_16x16x32_bf16 v[100:103], v[142:145], v[196:199], v[100:103]
	v_mfma_f32_16x16x32_bf16 v[96:99], v[150:153], v[196:199], v[96:99]
	v_mfma_f32_16x16x32_bf16 v[84:87], v[142:145], v[226:229], v[84:87]
	v_mfma_f32_16x16x32_bf16 v[80:83], v[150:153], v[226:229], v[80:83]
	v_mfma_f32_16x16x32_bf16 v[124:127], v[146:149], v[184:187], v[124:127]
	v_mfma_f32_16x16x32_bf16 v[120:123], v[154:157], v[184:187], v[120:123]
	v_mfma_f32_16x16x32_bf16 v[116:119], v[146:149], v[192:195], v[116:119]
	v_mfma_f32_16x16x32_bf16 v[112:115], v[154:157], v[192:195], v[112:115]
	v_mfma_f32_16x16x32_bf16 v[100:103], v[146:149], v[222:225], v[100:103]
	v_mfma_f32_16x16x32_bf16 v[96:99], v[154:157], v[222:225], v[96:99]
	v_mfma_f32_16x16x32_bf16 v[84:87], v[146:149], v[230:233], v[84:87]
	v_mfma_f32_16x16x32_bf16 v[80:83], v[154:157], v[230:233], v[80:83]
	s_setprio 0
	s_setprio 1
	v_mfma_f32_16x16x32_bf16 v[108:111], v[164:167], v[180:183], v[108:111]
	v_mfma_f32_16x16x32_bf16 v[104:107], v[172:175], v[180:183], v[104:107]
	v_mfma_f32_16x16x32_bf16 v[92:95], v[164:167], v[188:191], v[92:95]
	v_mfma_f32_16x16x32_bf16 v[88:91], v[172:175], v[188:191], v[88:91]
	v_mfma_f32_16x16x32_bf16 v[76:79], v[164:167], v[196:199], v[76:79]
	v_mfma_f32_16x16x32_bf16 v[72:75], v[172:175], v[196:199], v[72:75]
	v_mfma_f32_16x16x32_bf16 v[68:71], v[164:167], v[226:229], v[68:71]
	v_mfma_f32_16x16x32_bf16 v[64:67], v[172:175], v[226:229], v[64:67]
	v_mfma_f32_16x16x32_bf16 v[108:111], v[168:171], v[184:187], v[108:111]
	v_mfma_f32_16x16x32_bf16 v[104:107], v[176:179], v[184:187], v[104:107]
	v_mfma_f32_16x16x32_bf16 v[92:95], v[168:171], v[192:195], v[92:95]
	v_mfma_f32_16x16x32_bf16 v[88:91], v[176:179], v[192:195], v[88:91]
	v_mfma_f32_16x16x32_bf16 v[76:79], v[168:171], v[222:225], v[76:79]
	v_mfma_f32_16x16x32_bf16 v[72:75], v[176:179], v[222:225], v[72:75]
	v_mfma_f32_16x16x32_bf16 v[68:71], v[168:171], v[230:233], v[68:71]
	v_mfma_f32_16x16x32_bf16 v[64:67], v[176:179], v[230:233], v[64:67]
	s_setprio 0
	s_barrier
	s_add_i32 s56, s72, s24
	s_mov_b32 m0, s56
	ds_read_b128 v[180:183], v141 offset:49152
	ds_read_b128 v[184:187], v141 offset:50176
	ds_read_b128 v[188:191], v141 offset:51200
	ds_read_b128 v[192:195], v141 offset:52224
	ds_read_b128 v[196:199], v141 offset:53248
	ds_read_b128 v[222:225], v141 offset:54272
	ds_read_b128 v[226:229], v141 offset:55296
	ds_read_b128 v[230:233], v141 offset:56320
	s_add_u32 s52, s52, 0x80
	s_addc_u32 s53, s53, 0
	global_load_lds_dwordx4 v160, s[52:53]
	s_add_i32 m0, s56, 0x2000
	s_add_i32 s56, s73, s24
	global_load_lds_dwordx4 v128, s[52:53]
	s_add_u32 s52, s52, 0x160000
	s_addc_u32 s53, s53, 0
	s_mov_b32 m0, s56
	s_nop 0
	global_load_lds_dwordx4 v160, s[52:53]
	s_add_i32 m0, s56, 0x2000
	s_nop 0
	global_load_lds_dwordx4 v128, s[52:53]
	s_mov_b32 m0, s74
	s_nop 0
	global_load_lds_dwordx4 v132, s[98:99]
	s_mov_b32 m0, s75
	s_nop 0
	global_load_lds_dwordx4 v130, s[98:99]
	s_waitcnt vmcnt(8)
	s_waitcnt lgkmcnt(0)
	s_barrier
	s_setprio 1
	s_waitcnt lgkmcnt(0)
	v_mfma_f32_16x16x32_bf16 v[60:63], v[142:145], v[180:183], v[60:63]
	v_mfma_f32_16x16x32_bf16 v[56:59], v[150:153], v[180:183], v[56:59]
	v_mfma_f32_16x16x32_bf16 v[52:55], v[142:145], v[188:191], v[52:55]
	v_mfma_f32_16x16x32_bf16 v[48:51], v[150:153], v[188:191], v[48:51]
	v_mfma_f32_16x16x32_bf16 v[36:39], v[142:145], v[196:199], v[36:39]
	v_mfma_f32_16x16x32_bf16 v[32:35], v[150:153], v[196:199], v[32:35]
	v_mfma_f32_16x16x32_bf16 v[20:23], v[142:145], v[226:229], v[20:23]
	v_mfma_f32_16x16x32_bf16 v[16:19], v[150:153], v[226:229], v[16:19]
	v_mfma_f32_16x16x32_bf16 v[60:63], v[146:149], v[184:187], v[60:63]
	v_mfma_f32_16x16x32_bf16 v[56:59], v[154:157], v[184:187], v[56:59]
	v_mfma_f32_16x16x32_bf16 v[52:55], v[146:149], v[192:195], v[52:55]
	v_mfma_f32_16x16x32_bf16 v[48:51], v[154:157], v[192:195], v[48:51]
	v_mfma_f32_16x16x32_bf16 v[36:39], v[146:149], v[222:225], v[36:39]
	v_mfma_f32_16x16x32_bf16 v[32:35], v[154:157], v[222:225], v[32:35]
	v_mfma_f32_16x16x32_bf16 v[20:23], v[146:149], v[230:233], v[20:23]
	v_mfma_f32_16x16x32_bf16 v[16:19], v[154:157], v[230:233], v[16:19]
	s_setprio 0
	s_setprio 1
	v_mfma_f32_16x16x32_bf16 v[44:47], v[164:167], v[180:183], v[44:47]
	v_mfma_f32_16x16x32_bf16 v[40:43], v[172:175], v[180:183], v[40:43]
	v_mfma_f32_16x16x32_bf16 v[28:31], v[164:167], v[188:191], v[28:31]
	v_mfma_f32_16x16x32_bf16 v[24:27], v[172:175], v[188:191], v[24:27]
	v_mfma_f32_16x16x32_bf16 v[12:15], v[164:167], v[196:199], v[12:15]
	v_mfma_f32_16x16x32_bf16 v[8:11], v[172:175], v[196:199], v[8:11]
	v_mfma_f32_16x16x32_bf16 v[4:7], v[164:167], v[226:229], v[4:7]
	v_mfma_f32_16x16x32_bf16 v[0:3], v[172:175], v[226:229], v[0:3]
	v_mfma_f32_16x16x32_bf16 v[44:47], v[168:171], v[184:187], v[44:47]
	v_mfma_f32_16x16x32_bf16 v[40:43], v[176:179], v[184:187], v[40:43]
	v_mfma_f32_16x16x32_bf16 v[28:31], v[168:171], v[192:195], v[28:31]
	v_mfma_f32_16x16x32_bf16 v[24:27], v[176:179], v[192:195], v[24:27]
	v_mfma_f32_16x16x32_bf16 v[12:15], v[168:171], v[222:225], v[12:15]
	v_mfma_f32_16x16x32_bf16 v[8:11], v[176:179], v[222:225], v[8:11]
	v_mfma_f32_16x16x32_bf16 v[4:7], v[168:171], v[230:233], v[4:7]
	v_mfma_f32_16x16x32_bf16 v[0:3], v[176:179], v[230:233], v[0:3]
	s_setprio 0
	s_barrier
	s_add_i32 s83, s83, 2
	s_add_u32 s81, s81, 0x100
	s_addc_u32 s82, s82, 0
	s_cmpk_gt_u32 s83, 0x55
	s_mov_b64 s[72:73], s[4:5]
	s_cbranch_scc0 .LBB0_52
	s_and_b64 vcc, exec, s[42:43]
	s_cbranch_vccz .LBB0_55
	s_barrier

;     __host__ __device__ bool next(int i, Unit& u) const { if (!base.next(i >> 1, u)) return false; if (i & 1) { u.pm += 64; u.pn += 8; } return true; }
; #define PG8_STAGE(bufoff, gbase, voff) do { _Pragma("unroll") for (int _i = 0; _i < 2; ++_i) \
;         __builtin_amdgcn_global_load_lds((const unsigned*)((const char*)(gbase) + (voff)[_i]), (PG8_LAS unsigned*)(lds + (bufoff) + ldsw + _i * 8192), 16, 0, 0); } while (0)
; #define PG8_LDA(dst, b, h) do { _Pragma("unroll") for (int m = 0; m < 4; ++m) _Pragma("unroll") for (int k = 0; k < 2; ++k) dst[m][k] = *(const PG8_LAS bf16x8*)(lds + PG8_SA(b, h) + aoff + m * 2048 + k * 1024); } while (0)
; #define PG8_LDB(dst, b, h) do { _Pragma("unroll") for (int n = 0; n < 2; ++n) _Pragma("unroll") for (int k = 0; k < 2; ++k) dst[n][k] = *(const PG8_LAS bf16x8*)(lds + PG8_SB(b, h) + boff + n * 2048 + k * 1024); } while (0)
; #define PG8_WAIT_V(n) asm volatile("s_waitcnt vmcnt(" #n ")" ::: "memory")
; #define PG8_BAR __builtin_amdgcn_s_barrier()
; template <class Epi, class Sched, bool ALIGN_EPI = false, bool SP2 = false>
; __device__ __forceinline__ void gemm_phase(PG8_LAS unsigned char* lds, const Gemm g, const Sched& S, const Epi& E) {
;     ...
;         const bool has_next = S.next(ui + 1, nxt);
;         const char* nA = has_next ? (const char*)g.A + (size_t)nxt.pm * tstep : cA; const char* nB = has_next ? (const char*)g.Bt + (size_t)nxt.pn * tstep : cB;
;         for (int t = 0; t < nt; t += 2) {
;             const bool last = (t == nt - 2);
;             const char* a1 = cA + (size_t)(t + 1) * kstep;
;             const char* a2 = last ? nA : cA + (size_t)(t + 2) * kstep; const char* b2 = last ? nB : cB + (size_t)(t + 2) * kstep;
;             const char* a3 = a2 + kstep; const char* b3 = b2 + kstep;
;             if (last && has_next) S.a_ready(nxt);
;             if constexpr (SP2) {
;             PG8_LDB(B0, 0, 0); PG8_LDB(B1, 0, 1); PG8_SCHED; PG8_LDA(At, 0, 0); PG8_STAGE(PG8_SA(1, 1), a1 + hstep, voffA);
;             PG8_WAIT_V(8); PG8_WAIT_L(0); PG8_BAR; PG8_MMA(0, 0, At, B0); PG8_MMA(0, 1, At, B1); PG8_BAR; PG8_SCHED;
;     ...
;         for (int a = 0; a < 2; ++a)
; #pragma unroll
;             for (int b = 0; b < 2; ++b)
; #pragma unroll
;                 for (int m = 0; m < 4; ++m)
; #pragma unroll
;                     for (int n = 0; n < 2; ++n) acc[a][b][m][n] = (f32x4){0.f, 0.f, 0.f, 0.f};
.LBB0_85:
	s_bitcmp0_b32 s7, 0
	s_cselect_b64 s[28:29], -1, 0
	s_and_b64 s[28:29], s[28:29], s[44:45]
	s_add_i32 s7, s14, 64
	s_add_i32 s15, s42, 8
	s_and_b64 s[28:29], s[28:29], exec
	s_cselect_b32 s14, s7, s14
	s_cselect_b32 s42, s15, s42
	s_ashr_i32 s15, s14, 31
	s_lshl_b64 s[28:29], s[14:15], 19
	s_add_u32 s54, s56, s28
	s_addc_u32 s55, s57, s29
	s_and_b64 s[28:29], s[44:45], exec
	s_cselect_b32 s7, s55, s53
	s_cselect_b32 s15, s54, s52
	s_ashr_i32 s43, s42, 31
	s_lshl_b64 s[28:29], s[42:43], 19
	s_add_u32 s78, s0, s28
	s_addc_u32 s79, s1, s29
	s_and_b64 s[28:29], s[44:45], exec
	s_cselect_b32 s24, s79, s5
	s_cselect_b32 s28, s78, s4
	s_add_u32 s82, s52, 0x40080
	s_addc_u32 s83, s53, 0
	s_add_u32 s29, s4, 0x100
	v_mov_b32_e32 v0, 0
	s_addc_u32 s43, s5, 0
	s_mov_b32 s87, -2
	v_add_u32_e32 v200, 0x10000, v147
	v_mov_b32_e32 v1, v0
	v_mov_b32_e32 v2, v0
	v_mov_b32_e32 v3, v0
	v_mov_b32_e32 v4, v0
	v_mov_b32_e32 v5, v0
	v_mov_b32_e32 v6, v0
	v_mov_b32_e32 v7, v0
	v_mov_b32_e32 v16, v0
	v_mov_b32_e32 v17, v0
	v_mov_b32_e32 v18, v0
	v_mov_b32_e32 v19, v0
	v_mov_b32_e32 v20, v0
	v_mov_b32_e32 v21, v0
	v_mov_b32_e32 v22, v0
	v_mov_b32_e32 v23, v0
	v_mov_b32_e32 v32, v0
	v_mov_b32_e32 v33, v0
	v_mov_b32_e32 v34, v0
	v_mov_b32_e32 v35, v0
	v_mov_b32_e32 v36, v0
	v_mov_b32_e32 v37, v0
	v_mov_b32_e32 v38, v0
	v_mov_b32_e32 v39, v0
	v_mov_b32_e32 v48, v0
	v_mov_b32_e32 v49, v0
	v_mov_b32_e32 v50, v0
	v_mov_b32_e32 v51, v0
	v_mov_b32_e32 v52, v0
	v_mov_b32_e32 v53, v0
	v_mov_b32_e32 v54, v0
	v_mov_b32_e32 v55, v0
	v_mov_b32_e32 v8, v0
	v_mov_b32_e32 v9, v0
	v_mov_b32_e32 v10, v0
	v_mov_b32_e32 v11, v0
	v_mov_b32_e32 v12, v0
	v_mov_b32_e32 v13, v0
	v_mov_b32_e32 v14, v0
	v_mov_b32_e32 v15, v0
	v_mov_b32_e32 v24, v0
	v_mov_b32_e32 v25, v0
	v_mov_b32_e32 v26, v0
	v_mov_b32_e32 v27, v0
	v_mov_b32_e32 v28, v0
	v_mov_b32_e32 v29, v0
	v_mov_b32_e32 v30, v0
	v_mov_b32_e32 v31, v0
	v_mov_b32_e32 v40, v0
	v_mov_b32_e32 v41, v0
	v_mov_b32_e32 v42, v0
	v_mov_b32_e32 v43, v0
	v_mov_b32_e32 v44, v0
	v_mov_b32_e32 v45, v0
	v_mov_b32_e32 v46, v0
	v_mov_b32_e32 v47, v0
	v_mov_b32_e32 v56, v0
	v_mov_b32_e32 v57, v0
	v_mov_b32_e32 v58, v0
	v_mov_b32_e32 v59, v0
	v_mov_b32_e32 v60, v0
	v_mov_b32_e32 v61, v0
	v_mov_b32_e32 v62, v0
	v_mov_b32_e32 v63, v0
	v_mov_b32_e32 v64, v0
	v_mov_b32_e32 v65, v0
	v_mov_b32_e32 v66, v0
	v_mov_b32_e32 v67, v0
	v_mov_b32_e32 v68, v0
	v_mov_b32_e32 v69, v0
	v_mov_b32_e32 v70, v0
	v_mov_b32_e32 v71, v0
	v_mov_b32_e32 v80, v0
	v_mov_b32_e32 v81, v0
	v_mov_b32_e32 v82, v0
	v_mov_b32_e32 v83, v0
	v_mov_b32_e32 v84, v0
	v_mov_b32_e32 v85, v0
	v_mov_b32_e32 v86, v0
	v_mov_b32_e32 v87, v0
	v_mov_b32_e32 v96, v0
	v_mov_b32_e32 v97, v0
	v_mov_b32_e32 v98, v0
	v_mov_b32_e32 v99, v0
	v_mov_b32_e32 v100, v0
	v_mov_b32_e32 v101, v0
	v_mov_b32_e32 v102, v0
	v_mov_b32_e32 v103, v0
	v_mov_b32_e32 v112, v0
	v_mov_b32_e32 v113, v0
	v_mov_b32_e32 v114, v0
	v_mov_b32_e32 v115, v0
	v_mov_b32_e32 v116, v0
	v_mov_b32_e32 v117, v0
	v_mov_b32_e32 v118, v0
	v_mov_b32_e32 v119, v0
	v_mov_b32_e32 v72, v0
	v_mov_b32_e32 v73, v0
	v_mov_b32_e32 v74, v0
	v_mov_b32_e32 v75, v0
	v_mov_b32_e32 v76, v0
	v_mov_b32_e32 v77, v0
	v_mov_b32_e32 v78, v0
	v_mov_b32_e32 v79, v0
	v_mov_b32_e32 v88, v0
	v_mov_b32_e32 v89, v0
	v_mov_b32_e32 v90, v0
	v_mov_b32_e32 v91, v0
	v_mov_b32_e32 v92, v0
	v_mov_b32_e32 v93, v0
	v_mov_b32_e32 v94, v0
	v_mov_b32_e32 v95, v0
	v_mov_b32_e32 v104, v0
	v_mov_b32_e32 v105, v0
	v_mov_b32_e32 v106, v0
	v_mov_b32_e32 v107, v0
	v_mov_b32_e32 v108, v0
	v_mov_b32_e32 v109, v0
	v_mov_b32_e32 v110, v0
	v_mov_b32_e32 v111, v0
	v_mov_b32_e32 v120, v0
	v_mov_b32_e32 v121, v0
	v_mov_b32_e32 v122, v0
	v_mov_b32_e32 v123, v0
	v_mov_b32_e32 v124, v0
	v_mov_b32_e32 v125, v0
	v_mov_b32_e32 v126, v0
	v_mov_b32_e32 v127, v0
.LBB0_86:
	s_add_i32 s88, 0, 0x10000
	s_add_i32 s90, 0, 0x14000
	ds_read_b128 v[140:143], v200
	ds_read_b128 v[150:153], v200 offset:1024
	ds_read_b128 v[154:157], v200 offset:2048
	ds_read_b128 v[164:167], v200 offset:3072
	ds_read_b128 v[168:171], v200 offset:16384
	ds_read_b128 v[172:175], v200 offset:17408
	ds_read_b128 v[176:179], v200 offset:18432
	ds_read_b128 v[180:183], v200 offset:19456
	s_add_i32 m0, s63, 0xc000
	ds_read_b128 v[184:187], v149
	ds_read_b128 v[188:191], v149 offset:1024
	ds_read_b128 v[192:195], v149 offset:2048
	ds_read_b128 v[196:199], v149 offset:3072
	ds_read_b128 v[222:225], v149 offset:4096
	ds_read_b128 v[226:229], v149 offset:5120
	ds_read_b128 v[230:233], v149 offset:6144
	ds_read_b128 v[234:237], v149 offset:7168
	global_load_lds_dwordx4 v136, s[82:83]
	s_add_i32 m0, s63, 0xe000
	s_nop 0
	global_load_lds_dwordx4 v138, s[82:83]
	s_add_u32 s4, s82, 0xfffc0080
	s_addc_u32 s5, s83, -1
	s_cmp_eq_u32 s87, 12
	s_cselect_b32 s53, s7, s5
	s_cselect_b32 s52, s15, s4
	s_cselect_b32 s5, s24, s43
	s_cselect_b32 s4, s28, s29
	s_waitcnt vmcnt(8)
	s_waitcnt lgkmcnt(0)
	s_barrier
; #define PG8_STAGE(bufoff, gbase, voff) do { _Pragma("unroll") for (int _i = 0; _i < 2; ++_i) \
;         __builtin_amdgcn_global_load_lds((const unsigned*)((const char*)(gbase) + (voff)[_i]), (PG8_LAS unsigned*)(lds + (bufoff) + ldsw + _i * 8192), 16, 0, 0); } while (0)
; #define PG8_LDA(dst, b, h) do { _Pragma("unroll") for (int m = 0; m < 4; ++m) _Pragma("unroll") for (int k = 0; k < 2; ++k) dst[m][k] = *(const PG8_LAS bf16x8*)(lds + PG8_SA(b, h) + aoff + m * 2048 + k * 1024); } while (0)
; #define PG8_MMA(ai, bj, At, Bt) do { __builtin_amdgcn_s_setprio(1); _Pragma("unroll") for (int m = 0; m < 4; ++m) _Pragma("unroll") for (int n = 0; n < 2; ++n) _Pragma("unroll") for (int k = 0; k < 2; ++k) \
;         acc[ai][bj][m][n] = __builtin_amdgcn_mfma_f32_16x16x32_bf16(Bt[n][k], At[m][k], acc[ai][bj][m][n], 0, 0, 0); __builtin_amdgcn_s_setprio(0); } while (0)
; #define PG8_WAIT_V(n) asm volatile("s_waitcnt vmcnt(" #n ")" ::: "memory")
; #define PG8_WAIT_L(n) asm volatile("s_waitcnt lgkmcnt(" #n ")" ::: "memory")
; #define PG8_BAR __builtin_amdgcn_s_barrier()
; #define PG8_SCHED __builtin_amdgcn_sched_barrier(0)
; template <class Epi, class Sched, bool ALIGN_EPI = false, bool SP2 = false>
; __device__ __forceinline__ void gemm_phase(PG8_LAS unsigned char* lds, const Gemm g, const Sched& S, const Epi& E) {
;     ...
;             PG8_WAIT_V(8); PG8_WAIT_L(0); PG8_BAR; PG8_MMA(0, 0, At, B0); PG8_MMA(0, 1, At, B1); PG8_BAR; PG8_SCHED;
;             PG8_LDA(At, 0, 1); PG8_STAGE(PG8_SB(0, 0), b2, voffB); PG8_STAGE(PG8_SB(0, 1), b2 + hstep, voffB); PG8_STAGE(PG8_SA(0, 0), a2, voffA);
;             PG8_WAIT_V(8); PG8_WAIT_L(0); PG8_BAR; PG8_MMA(1, 0, At, B0); PG8_MMA(1, 1, At, B1); PG8_BAR; PG8_SCHED;
	s_setprio 1
	s_waitcnt lgkmcnt(0)
	v_mfma_f32_16x16x32_bf16 v[124:127], v[140:143], v[184:187], v[124:127]
	v_mfma_f32_16x16x32_bf16 v[120:123], v[154:157], v[184:187], v[120:123]
	v_mfma_f32_16x16x32_bf16 v[108:111], v[140:143], v[192:195], v[108:111]
	v_mfma_f32_16x16x32_bf16 v[104:107], v[154:157], v[192:195], v[104:107]
	v_mfma_f32_16x16x32_bf16 v[92:95], v[140:143], v[222:225], v[92:95]
	v_mfma_f32_16x16x32_bf16 v[88:91], v[154:157], v[222:225], v[88:91]
	v_mfma_f32_16x16x32_bf16 v[76:79], v[140:143], v[230:233], v[76:79]
	v_mfma_f32_16x16x32_bf16 v[72:75], v[154:157], v[230:233], v[72:75]
	v_mfma_f32_16x16x32_bf16 v[124:127], v[150:153], v[188:191], v[124:127]
	v_mfma_f32_16x16x32_bf16 v[120:123], v[164:167], v[188:191], v[120:123]
	v_mfma_f32_16x16x32_bf16 v[108:111], v[150:153], v[196:199], v[108:111]
	v_mfma_f32_16x16x32_bf16 v[104:107], v[164:167], v[196:199], v[104:107]
	v_mfma_f32_16x16x32_bf16 v[92:95], v[150:153], v[226:229], v[92:95]
	v_mfma_f32_16x16x32_bf16 v[88:91], v[164:167], v[226:229], v[88:91]
	v_mfma_f32_16x16x32_bf16 v[76:79], v[150:153], v[234:237], v[76:79]
	v_mfma_f32_16x16x32_bf16 v[72:75], v[164:167], v[234:237], v[72:75]
	s_setprio 0
	s_setprio 1
	v_mfma_f32_16x16x32_bf16 v[116:119], v[168:171], v[184:187], v[116:119]
	v_mfma_f32_16x16x32_bf16 v[112:115], v[176:179], v[184:187], v[112:115]
	v_mfma_f32_16x16x32_bf16 v[100:103], v[168:171], v[192:195], v[100:103]
	v_mfma_f32_16x16x32_bf16 v[96:99], v[176:179], v[192:195], v[96:99]
	v_mfma_f32_16x16x32_bf16 v[84:87], v[168:171], v[222:225], v[84:87]
	v_mfma_f32_16x16x32_bf16 v[80:83], v[176:179], v[222:225], v[80:83]
	v_mfma_f32_16x16x32_bf16 v[68:71], v[168:171], v[230:233], v[68:71]
	v_mfma_f32_16x16x32_bf16 v[64:67], v[176:179], v[230:233], v[64:67]
	v_mfma_f32_16x16x32_bf16 v[116:119], v[172:175], v[188:191], v[116:119]
	v_mfma_f32_16x16x32_bf16 v[112:115], v[180:183], v[188:191], v[112:115]
	v_mfma_f32_16x16x32_bf16 v[100:103], v[172:175], v[196:199], v[100:103]
	v_mfma_f32_16x16x32_bf16 v[96:99], v[180:183], v[196:199], v[96:99]
	v_mfma_f32_16x16x32_bf16 v[84:87], v[172:175], v[226:229], v[84:87]
	v_mfma_f32_16x16x32_bf16 v[80:83], v[180:183], v[226:229], v[80:83]
	v_mfma_f32_16x16x32_bf16 v[68:71], v[172:175], v[234:237], v[68:71]
	v_mfma_f32_16x16x32_bf16 v[64:67], v[180:183], v[234:237], v[64:67]
	s_setprio 0
	s_barrier
	s_add_i32 s88, s88, s59
	s_mov_b32 m0, s88
	ds_read_b128 v[184:187], v149 offset:16384
	ds_read_b128 v[188:191], v149 offset:17408
	ds_read_b128 v[192:195], v149 offset:18432
	ds_read_b128 v[196:199], v149 offset:19456
	ds_read_b128 v[222:225], v149 offset:20480
	ds_read_b128 v[226:229], v149 offset:21504
	ds_read_b128 v[230:233], v149 offset:22528
	ds_read_b128 v[234:237], v149 offset:23552
	global_load_lds_dwordx4 v130, s[4:5]
	s_add_i32 m0, s88, 0x2000
	s_add_u32 s88, s4, 0x40000
	s_addc_u32 s89, s5, 0
	s_add_i32 s90, s90, s59
	global_load_lds_dwordx4 v134, s[4:5]
	s_mov_b32 m0, s90
	s_nop 0
	global_load_lds_dwordx4 v130, s[88:89]
	s_add_i32 m0, s90, 0x2000
	s_nop 0
	global_load_lds_dwordx4 v134, s[88:89]
	s_mov_b32 m0, s63
	s_nop 0
	global_load_lds_dwordx4 v128, s[52:53]
	s_mov_b32 m0, s74
	s_nop 0
	global_load_lds_dwordx4 v132, s[52:53]
	s_add_u32 s98, s52, 0x80
	s_addc_u32 s99, s53, 0
	s_waitcnt vmcnt(8)
	s_waitcnt lgkmcnt(0)
	s_barrier
	s_setprio 1
	s_waitcnt lgkmcnt(0)
	v_mfma_f32_16x16x32_bf16 v[60:63], v[140:143], v[184:187], v[60:63]
	v_mfma_f32_16x16x32_bf16 v[56:59], v[154:157], v[184:187], v[56:59]
	v_mfma_f32_16x16x32_bf16 v[44:47], v[140:143], v[192:195], v[44:47]
	v_mfma_f32_16x16x32_bf16 v[40:43], v[154:157], v[192:195], v[40:43]
	v_mfma_f32_16x16x32_bf16 v[28:31], v[140:143], v[222:225], v[28:31]
	v_mfma_f32_16x16x32_bf16 v[24:27], v[154:157], v[222:225], v[24:27]
	v_mfma_f32_16x16x32_bf16 v[12:15], v[140:143], v[230:233], v[12:15]
	v_mfma_f32_16x16x32_bf16 v[8:11], v[154:157], v[230:233], v[8:11]
	v_mfma_f32_16x16x32_bf16 v[60:63], v[150:153], v[188:191], v[60:63]
	v_mfma_f32_16x16x32_bf16 v[56:59], v[164:167], v[188:191], v[56:59]
	v_mfma_f32_16x16x32_bf16 v[44:47], v[150:153], v[196:199], v[44:47]
	v_mfma_f32_16x16x32_bf16 v[40:43], v[164:167], v[196:199], v[40:43]
	v_mfma_f32_16x16x32_bf16 v[28:31], v[150:153], v[226:229], v[28:31]
	v_mfma_f32_16x16x32_bf16 v[24:27], v[164:167], v[226:229], v[24:27]
	v_mfma_f32_16x16x32_bf16 v[12:15], v[150:153], v[234:237], v[12:15]
	v_mfma_f32_16x16x32_bf16 v[8:11], v[164:167], v[234:237], v[8:11]
	s_setprio 0
	s_setprio 1
	v_mfma_f32_16x16x32_bf16 v[52:55], v[168:171], v[184:187], v[52:55]
	v_mfma_f32_16x16x32_bf16 v[48:51], v[176:179], v[184:187], v[48:51]
	v_mfma_f32_16x16x32_bf16 v[36:39], v[168:171], v[192:195], v[36:39]
	v_mfma_f32_16x16x32_bf16 v[32:35], v[176:179], v[192:195], v[32:35]
	v_mfma_f32_16x16x32_bf16 v[20:23], v[168:171], v[222:225], v[20:23]
	v_mfma_f32_16x16x32_bf16 v[16:19], v[176:179], v[222:225], v[16:19]
	v_mfma_f32_16x16x32_bf16 v[4:7], v[168:171], v[230:233], v[4:7]
	v_mfma_f32_16x16x32_bf16 v[0:3], v[176:179], v[230:233], v[0:3]
	v_mfma_f32_16x16x32_bf16 v[52:55], v[172:175], v[188:191], v[52:55]
	v_mfma_f32_16x16x32_bf16 v[48:51], v[180:183], v[188:191], v[48:51]
	v_mfma_f32_16x16x32_bf16 v[36:39], v[172:175], v[196:199], v[36:39]
	v_mfma_f32_16x16x32_bf16 v[32:35], v[180:183], v[196:199], v[32:35]
	v_mfma_f32_16x16x32_bf16 v[20:23], v[172:175], v[226:229], v[20:23]
	v_mfma_f32_16x16x32_bf16 v[16:19], v[180:183], v[226:229], v[16:19]
	v_mfma_f32_16x16x32_bf16 v[4:7], v[172:175], v[234:237], v[4:7]
	v_mfma_f32_16x16x32_bf16 v[0:3], v[180:183], v[234:237], v[0:3]
	s_setprio 0
	s_barrier
; #define PG8_STAGE(bufoff, gbase, voff) do { _Pragma("unroll") for (int _i = 0; _i < 2; ++_i) \
;         __builtin_amdgcn_global_load_lds((const unsigned*)((const char*)(gbase) + (voff)[_i]), (PG8_LAS unsigned*)(lds + (bufoff) + ldsw + _i * 8192), 16, 0, 0); } while (0)
; #define PG8_LDA(dst, b, h) do { _Pragma("unroll") for (int m = 0; m < 4; ++m) _Pragma("unroll") for (int k = 0; k < 2; ++k) dst[m][k] = *(const PG8_LAS bf16x8*)(lds + PG8_SA(b, h) + aoff + m * 2048 + k * 1024); } while (0)
; #define PG8_LDB(dst, b, h) do { _Pragma("unroll") for (int n = 0; n < 2; ++n) _Pragma("unroll") for (int k = 0; k < 2; ++k) dst[n][k] = *(const PG8_LAS bf16x8*)(lds + PG8_SB(b, h) + boff + n * 2048 + k * 1024); } while (0)
; #define PG8_MMA(ai, bj, At, Bt) do { __builtin_amdgcn_s_setprio(1); _Pragma("unroll") for (int m = 0; m < 4; ++m) _Pragma("unroll") for (int n = 0; n < 2; ++n) _Pragma("unroll") for (int k = 0; k < 2; ++k) \
;         acc[ai][bj][m][n] = __builtin_amdgcn_mfma_f32_16x16x32_bf16(Bt[n][k], At[m][k], acc[ai][bj][m][n], 0, 0, 0); __builtin_amdgcn_s_setprio(0); } while (0)
; #define PG8_WAIT_V(n) asm volatile("s_waitcnt vmcnt(" #n ")" ::: "memory")
; #define PG8_WAIT_L(n) asm volatile("s_waitcnt lgkmcnt(" #n ")" ::: "memory")
; #define PG8_BAR __builtin_amdgcn_s_barrier()
; #define PG8_SCHED __builtin_amdgcn_sched_barrier(0)
; template <class Epi, class Sched, bool ALIGN_EPI = false, bool SP2 = false>
; __device__ __forceinline__ void gemm_phase(PG8_LAS unsigned char* lds, const Gemm g, const Sched& S, const Epi& E) {
;     ...
;             PG8_LDB(B0, 1, 0); PG8_LDB(B1, 1, 1); PG8_SCHED; PG8_LDA(At, 1, 0); PG8_STAGE(PG8_SA(0, 1), a2 + hstep, voffA);
;             PG8_WAIT_V(8); PG8_WAIT_L(0); PG8_BAR; PG8_MMA(0, 0, At, B0); PG8_MMA(0, 1, At, B1); PG8_BAR; PG8_SCHED;
;             PG8_LDA(At, 1, 1); PG8_STAGE(PG8_SB(1, 0), b3, voffB); PG8_STAGE(PG8_SB(1, 1), b3 + hstep, voffB); PG8_STAGE(PG8_SA(1, 0), a3, voffA);
;             PG8_WAIT_V(8); PG8_WAIT_L(0); PG8_BAR; PG8_MMA(1, 0, At, B0); PG8_MMA(1, 1, At, B1); PG8_BAR; PG8_SCHED;
	s_add_i32 s88, 0, 0x18000
	s_add_i32 s89, 0, 0x1c000
	ds_read_b128 v[140:143], v200 offset:32768
	ds_read_b128 v[150:153], v200 offset:33792
	ds_read_b128 v[154:157], v200 offset:34816
	ds_read_b128 v[164:167], v200 offset:35840
	ds_read_b128 v[168:171], v200 offset:49152
	ds_read_b128 v[172:175], v200 offset:50176
	ds_read_b128 v[176:179], v200 offset:51200
	ds_read_b128 v[180:183], v200 offset:52224
	s_add_u32 s52, s52, 0x40000
	s_addc_u32 s53, s53, 0
	s_mov_b32 m0, s75
	ds_read_b128 v[184:187], v149 offset:32768
	ds_read_b128 v[188:191], v149 offset:33792
	ds_read_b128 v[192:195], v149 offset:34816
	ds_read_b128 v[196:199], v149 offset:35840
	ds_read_b128 v[222:225], v149 offset:36864
	ds_read_b128 v[226:229], v149 offset:37888
	ds_read_b128 v[230:233], v149 offset:38912
	ds_read_b128 v[234:237], v149 offset:39936
	global_load_lds_dwordx4 v128, s[52:53]
	s_mov_b32 m0, s81
	s_nop 0
	global_load_lds_dwordx4 v132, s[52:53]
	s_waitcnt vmcnt(8)
	s_waitcnt lgkmcnt(0)
	s_barrier
	s_setprio 1
	s_waitcnt lgkmcnt(0)
	v_mfma_f32_16x16x32_bf16 v[124:127], v[140:143], v[184:187], v[124:127]
	v_mfma_f32_16x16x32_bf16 v[120:123], v[154:157], v[184:187], v[120:123]
	v_mfma_f32_16x16x32_bf16 v[108:111], v[140:143], v[192:195], v[108:111]
	v_mfma_f32_16x16x32_bf16 v[104:107], v[154:157], v[192:195], v[104:107]
	v_mfma_f32_16x16x32_bf16 v[92:95], v[140:143], v[222:225], v[92:95]
	v_mfma_f32_16x16x32_bf16 v[88:91], v[154:157], v[222:225], v[88:91]
	v_mfma_f32_16x16x32_bf16 v[76:79], v[140:143], v[230:233], v[76:79]
	v_mfma_f32_16x16x32_bf16 v[72:75], v[154:157], v[230:233], v[72:75]
	v_mfma_f32_16x16x32_bf16 v[124:127], v[150:153], v[188:191], v[124:127]
	v_mfma_f32_16x16x32_bf16 v[120:123], v[164:167], v[188:191], v[120:123]
	v_mfma_f32_16x16x32_bf16 v[108:111], v[150:153], v[196:199], v[108:111]
	v_mfma_f32_16x16x32_bf16 v[104:107], v[164:167], v[196:199], v[104:107]
	v_mfma_f32_16x16x32_bf16 v[92:95], v[150:153], v[226:229], v[92:95]
	v_mfma_f32_16x16x32_bf16 v[88:91], v[164:167], v[226:229], v[88:91]
	v_mfma_f32_16x16x32_bf16 v[76:79], v[150:153], v[234:237], v[76:79]
	v_mfma_f32_16x16x32_bf16 v[72:75], v[164:167], v[234:237], v[72:75]
	s_setprio 0
	s_setprio 1
	v_mfma_f32_16x16x32_bf16 v[116:119], v[168:171], v[184:187], v[116:119]
	v_mfma_f32_16x16x32_bf16 v[112:115], v[176:179], v[184:187], v[112:115]
	v_mfma_f32_16x16x32_bf16 v[100:103], v[168:171], v[192:195], v[100:103]
	v_mfma_f32_16x16x32_bf16 v[96:99], v[176:179], v[192:195], v[96:99]
	v_mfma_f32_16x16x32_bf16 v[84:87], v[168:171], v[222:225], v[84:87]
	v_mfma_f32_16x16x32_bf16 v[80:83], v[176:179], v[222:225], v[80:83]
	v_mfma_f32_16x16x32_bf16 v[68:71], v[168:171], v[230:233], v[68:71]
	v_mfma_f32_16x16x32_bf16 v[64:67], v[176:179], v[230:233], v[64:67]
	v_mfma_f32_16x16x32_bf16 v[116:119], v[172:175], v[188:191], v[116:119]
	v_mfma_f32_16x16x32_bf16 v[112:115], v[180:183], v[188:191], v[112:115]
	v_mfma_f32_16x16x32_bf16 v[100:103], v[172:175], v[196:199], v[100:103]
	v_mfma_f32_16x16x32_bf16 v[96:99], v[180:183], v[196:199], v[96:99]
	v_mfma_f32_16x16x32_bf16 v[84:87], v[172:175], v[226:229], v[84:87]
	v_mfma_f32_16x16x32_bf16 v[80:83], v[180:183], v[226:229], v[80:83]
	v_mfma_f32_16x16x32_bf16 v[68:71], v[172:175], v[234:237], v[68:71]
	v_mfma_f32_16x16x32_bf16 v[64:67], v[180:183], v[234:237], v[64:67]
	s_setprio 0
	s_barrier
	s_add_i32 s52, s88, s59
	s_mov_b32 m0, s52
	ds_read_b128 v[184:187], v149 offset:49152
	ds_read_b128 v[188:191], v149 offset:50176
	ds_read_b128 v[192:195], v149 offset:51200
	ds_read_b128 v[196:199], v149 offset:52224
	ds_read_b128 v[222:225], v149 offset:53248
	ds_read_b128 v[226:229], v149 offset:54272
	ds_read_b128 v[230:233], v149 offset:55296
	ds_read_b128 v[234:237], v149 offset:56320
	s_add_u32 s4, s4, 0x80
	s_addc_u32 s5, s5, 0
	global_load_lds_dwordx4 v130, s[4:5]
	s_add_i32 m0, s52, 0x2000
	s_add_i32 s52, s89, s59
	global_load_lds_dwordx4 v134, s[4:5]
	s_add_u32 s4, s4, 0x40000
	s_addc_u32 s5, s5, 0
	s_mov_b32 m0, s52
	s_nop 0
	global_load_lds_dwordx4 v130, s[4:5]
	s_add_i32 m0, s52, 0x2000
	s_nop 0
	global_load_lds_dwordx4 v134, s[4:5]
	s_mov_b32 m0, s84
	s_nop 0
	global_load_lds_dwordx4 v128, s[98:99]
	s_mov_b32 m0, s85
	s_nop 0
	global_load_lds_dwordx4 v132, s[98:99]
	s_waitcnt vmcnt(8)
	s_waitcnt lgkmcnt(0)
	s_barrier
	s_setprio 1
	s_waitcnt lgkmcnt(0)
	v_mfma_f32_16x16x32_bf16 v[60:63], v[140:143], v[184:187], v[60:63]
	v_mfma_f32_16x16x32_bf16 v[56:59], v[154:157], v[184:187], v[56:59]
	v_mfma_f32_16x16x32_bf16 v[44:47], v[140:143], v[192:195], v[44:47]
	v_mfma_f32_16x16x32_bf16 v[40:43], v[154:157], v[192:195], v[40:43]
	v_mfma_f32_16x16x32_bf16 v[28:31], v[140:143], v[222:225], v[28:31]
	v_mfma_f32_16x16x32_bf16 v[24:27], v[154:157], v[222:225], v[24:27]
	v_mfma_f32_16x16x32_bf16 v[12:15], v[140:143], v[230:233], v[12:15]
	v_mfma_f32_16x16x32_bf16 v[8:11], v[154:157], v[230:233], v[8:11]
	v_mfma_f32_16x16x32_bf16 v[60:63], v[150:153], v[188:191], v[60:63]
	v_mfma_f32_16x16x32_bf16 v[56:59], v[164:167], v[188:191], v[56:59]
	v_mfma_f32_16x16x32_bf16 v[44:47], v[150:153], v[196:199], v[44:47]
	v_mfma_f32_16x16x32_bf16 v[40:43], v[164:167], v[196:199], v[40:43]
	v_mfma_f32_16x16x32_bf16 v[28:31], v[150:153], v[226:229], v[28:31]
	v_mfma_f32_16x16x32_bf16 v[24:27], v[164:167], v[226:229], v[24:27]
	v_mfma_f32_16x16x32_bf16 v[12:15], v[150:153], v[234:237], v[12:15]
	v_mfma_f32_16x16x32_bf16 v[8:11], v[164:167], v[234:237], v[8:11]
	s_setprio 0
	s_setprio 1
	v_mfma_f32_16x16x32_bf16 v[52:55], v[168:171], v[184:187], v[52:55]
	v_mfma_f32_16x16x32_bf16 v[48:51], v[176:179], v[184:187], v[48:51]
	v_mfma_f32_16x16x32_bf16 v[36:39], v[168:171], v[192:195], v[36:39]
	v_mfma_f32_16x16x32_bf16 v[32:35], v[176:179], v[192:195], v[32:35]
	v_mfma_f32_16x16x32_bf16 v[20:23], v[168:171], v[222:225], v[20:23]
	v_mfma_f32_16x16x32_bf16 v[16:19], v[176:179], v[222:225], v[16:19]
	v_mfma_f32_16x16x32_bf16 v[4:7], v[168:171], v[230:233], v[4:7]
	v_mfma_f32_16x16x32_bf16 v[0:3], v[176:179], v[230:233], v[0:3]
	v_mfma_f32_16x16x32_bf16 v[52:55], v[172:175], v[188:191], v[52:55]
	v_mfma_f32_16x16x32_bf16 v[48:51], v[180:183], v[188:191], v[48:51]
	v_mfma_f32_16x16x32_bf16 v[36:39], v[172:175], v[196:199], v[36:39]
	v_mfma_f32_16x16x32_bf16 v[32:35], v[180:183], v[196:199], v[32:35]
	v_mfma_f32_16x16x32_bf16 v[20:23], v[172:175], v[226:229], v[20:23]
	v_mfma_f32_16x16x32_bf16 v[16:19], v[180:183], v[226:229], v[16:19]
	v_mfma_f32_16x16x32_bf16 v[4:7], v[172:175], v[234:237], v[4:7]
	v_mfma_f32_16x16x32_bf16 v[0:3], v[180:183], v[234:237], v[0:3]
	s_setprio 0
	s_barrier
	s_add_i32 s87, s87, 2
	s_add_u32 s82, s82, 0x100
	s_addc_u32 s83, s83, 0
	s_add_u32 s29, s29, 0x100
	s_addc_u32 s43, s43, 0
	s_cmp_gt_u32 s87, 13
	s_cbranch_scc0 .LBB0_86
	s_and_b64 vcc, exec, s[12:13]
	s_cbranch_vccz .LBB0_89
	s_barrier

;     __host__ __device__ bool next(int i, Unit& u) const { if (!base.next(i >> 1, u)) return false; if (i & 1) { u.pm += 64; u.pn += 8; } return true; }
; #define PG8_STAGE(bufoff, gbase, voff) do { _Pragma("unroll") for (int _i = 0; _i < 2; ++_i) \
;         __builtin_amdgcn_global_load_lds((const unsigned*)((const char*)(gbase) + (voff)[_i]), (PG8_LAS unsigned*)(lds + (bufoff) + ldsw + _i * 8192), 16, 0, 0); } while (0)
; #define PG8_LDA(dst, b, h) do { _Pragma("unroll") for (int m = 0; m < 4; ++m) _Pragma("unroll") for (int k = 0; k < 2; ++k) dst[m][k] = *(const PG8_LAS bf16x8*)(lds + PG8_SA(b, h) + aoff + m * 2048 + k * 1024); } while (0)
; #define PG8_LDB(dst, b, h) do { _Pragma("unroll") for (int n = 0; n < 2; ++n) _Pragma("unroll") for (int k = 0; k < 2; ++k) dst[n][k] = *(const PG8_LAS bf16x8*)(lds + PG8_SB(b, h) + boff + n * 2048 + k * 1024); } while (0)
; #define PG8_WAIT_V(n) asm volatile("s_waitcnt vmcnt(" #n ")" ::: "memory")
; #define PG8_BAR __builtin_amdgcn_s_barrier()
; template <class Epi, class Sched, bool ALIGN_EPI = false, bool SP2 = false>
; __device__ __forceinline__ void gemm_phase(PG8_LAS unsigned char* lds, const Gemm g, const Sched& S, const Epi& E) {
;     ...
;         const bool has_next = S.next(ui + 1, nxt);
;         const char* nA = has_next ? (const char*)g.A + (size_t)nxt.pm * tstep : cA; const char* nB = has_next ? (const char*)g.Bt + (size_t)nxt.pn * tstep : cB;
;         for (int t = 0; t < nt; t += 2) {
;             const bool last = (t == nt - 2);
;             const char* a1 = cA + (size_t)(t + 1) * kstep;
;             const char* a2 = last ? nA : cA + (size_t)(t + 2) * kstep; const char* b2 = last ? nB : cB + (size_t)(t + 2) * kstep;
;             const char* a3 = a2 + kstep; const char* b3 = b2 + kstep;
;             if (last && has_next) S.a_ready(nxt);
;             if constexpr (SP2) {
;             PG8_LDB(B0, 0, 0); PG8_LDB(B1, 0, 1); PG8_SCHED; PG8_LDA(At, 0, 0); PG8_STAGE(PG8_SA(1, 1), a1 + hstep, voffA);
;             PG8_WAIT_V(8); PG8_WAIT_L(0); PG8_BAR; PG8_MMA(0, 0, At, B0); PG8_MMA(0, 1, At, B1); PG8_BAR; PG8_SCHED;
;     ...
;         for (int a = 0; a < 2; ++a)
; #pragma unroll
;             for (int b = 0; b < 2; ++b)
; #pragma unroll
;                 for (int m = 0; m < 4; ++m)
; #pragma unroll
;                     for (int n = 0; n < 2; ++n) acc[a][b][m][n] = (f32x4){0.f, 0.f, 0.f, 0.f};
.LBB0_321:
	s_ashr_i32 s43, s42, 31
	s_lshl_b64 s[28:29], s[42:43], 20
	s_add_u32 s94, s66, s28
	s_addc_u32 s95, s67, s29
	s_and_b64 s[28:29], s[92:93], exec
	s_cselect_b32 s1, s95, s15
	s_cselect_b32 s28, s94, s14
	s_ashr_i32 s45, s44, 31
	s_lshl_b64 s[52:53], s[44:45], 20
	s_add_u32 s96, s24, s52
	s_addc_u32 s97, s59, s53
	s_and_b64 s[52:53], s[92:93], exec
	s_cselect_b32 s29, s97, s5
	s_cselect_b32 s43, s96, s4
	s_add_u32 s14, s14, 0x80080
	s_addc_u32 s15, s15, 0
	s_add_u32 s45, s4, 0x100
	v_mov_b32_e32 v0, 0
	s_addc_u32 s54, s5, 0
	s_mov_b32 s55, -2
	v_add_u32_e32 v246, 0x10000, v139
	v_mov_b32_e32 v1, v0
	v_mov_b32_e32 v2, v0
	v_mov_b32_e32 v3, v0
	v_mov_b32_e32 v4, v0
	v_mov_b32_e32 v5, v0
	v_mov_b32_e32 v6, v0
	v_mov_b32_e32 v7, v0
	v_mov_b32_e32 v8, v0
	v_mov_b32_e32 v9, v0
	v_mov_b32_e32 v10, v0
	v_mov_b32_e32 v11, v0
	v_mov_b32_e32 v12, v0
	v_mov_b32_e32 v13, v0
	v_mov_b32_e32 v14, v0
	v_mov_b32_e32 v15, v0
	v_mov_b32_e32 v16, v0
	v_mov_b32_e32 v17, v0
	v_mov_b32_e32 v18, v0
	v_mov_b32_e32 v19, v0
	v_mov_b32_e32 v20, v0
	v_mov_b32_e32 v21, v0
	v_mov_b32_e32 v22, v0
	v_mov_b32_e32 v23, v0
	v_mov_b32_e32 v24, v0
	v_mov_b32_e32 v25, v0
	v_mov_b32_e32 v26, v0
	v_mov_b32_e32 v27, v0
	v_mov_b32_e32 v28, v0
	v_mov_b32_e32 v29, v0
	v_mov_b32_e32 v30, v0
	v_mov_b32_e32 v31, v0
	v_mov_b32_e32 v32, v0
	v_mov_b32_e32 v33, v0
	v_mov_b32_e32 v34, v0
	v_mov_b32_e32 v35, v0
	v_mov_b32_e32 v36, v0
	v_mov_b32_e32 v37, v0
	v_mov_b32_e32 v38, v0
	v_mov_b32_e32 v39, v0
	v_mov_b32_e32 v40, v0
	v_mov_b32_e32 v41, v0
	v_mov_b32_e32 v42, v0
	v_mov_b32_e32 v43, v0
	v_mov_b32_e32 v44, v0
	v_mov_b32_e32 v45, v0
	v_mov_b32_e32 v46, v0
	v_mov_b32_e32 v47, v0
	v_mov_b32_e32 v48, v0
	v_mov_b32_e32 v49, v0
	v_mov_b32_e32 v50, v0
	v_mov_b32_e32 v51, v0
	v_mov_b32_e32 v52, v0
	v_mov_b32_e32 v53, v0
	v_mov_b32_e32 v54, v0
	v_mov_b32_e32 v55, v0
	v_mov_b32_e32 v56, v0
	v_mov_b32_e32 v57, v0
	v_mov_b32_e32 v58, v0
	v_mov_b32_e32 v59, v0
	v_mov_b32_e32 v60, v0
	v_mov_b32_e32 v61, v0
	v_mov_b32_e32 v62, v0
	v_mov_b32_e32 v63, v0
	v_mov_b32_e32 v64, v0
	v_mov_b32_e32 v65, v0
	v_mov_b32_e32 v66, v0
	v_mov_b32_e32 v67, v0
	v_mov_b32_e32 v68, v0
	v_mov_b32_e32 v69, v0
	v_mov_b32_e32 v70, v0
	v_mov_b32_e32 v71, v0
	v_mov_b32_e32 v72, v0
	v_mov_b32_e32 v73, v0
	v_mov_b32_e32 v74, v0
	v_mov_b32_e32 v75, v0
	v_mov_b32_e32 v76, v0
	v_mov_b32_e32 v77, v0
	v_mov_b32_e32 v78, v0
	v_mov_b32_e32 v79, v0
	v_mov_b32_e32 v80, v0
	v_mov_b32_e32 v81, v0
	v_mov_b32_e32 v82, v0
	v_mov_b32_e32 v83, v0
	v_mov_b32_e32 v84, v0
	v_mov_b32_e32 v85, v0
	v_mov_b32_e32 v86, v0
	v_mov_b32_e32 v87, v0
	v_mov_b32_e32 v88, v0
	v_mov_b32_e32 v89, v0
	v_mov_b32_e32 v90, v0
	v_mov_b32_e32 v91, v0
	v_mov_b32_e32 v92, v0
	v_mov_b32_e32 v93, v0
	v_mov_b32_e32 v94, v0
	v_mov_b32_e32 v95, v0
	v_mov_b32_e32 v96, v0
	v_mov_b32_e32 v97, v0
	v_mov_b32_e32 v98, v0
	v_mov_b32_e32 v99, v0
	v_mov_b32_e32 v100, v0
	v_mov_b32_e32 v101, v0
	v_mov_b32_e32 v102, v0
	v_mov_b32_e32 v103, v0
	v_mov_b32_e32 v104, v0
	v_mov_b32_e32 v105, v0
	v_mov_b32_e32 v106, v0
	v_mov_b32_e32 v107, v0
	v_mov_b32_e32 v108, v0
	v_mov_b32_e32 v109, v0
	v_mov_b32_e32 v110, v0
	v_mov_b32_e32 v111, v0
	v_mov_b32_e32 v112, v0
	v_mov_b32_e32 v113, v0
	v_mov_b32_e32 v114, v0
	v_mov_b32_e32 v115, v0
	v_mov_b32_e32 v116, v0
	v_mov_b32_e32 v117, v0
	v_mov_b32_e32 v118, v0
	v_mov_b32_e32 v119, v0
	v_mov_b32_e32 v120, v0
	v_mov_b32_e32 v121, v0
	v_mov_b32_e32 v122, v0
	v_mov_b32_e32 v123, v0
	v_mov_b32_e32 v124, v0
	v_mov_b32_e32 v125, v0
	v_mov_b32_e32 v126, v0
	v_mov_b32_e32 v127, v0
.LBB0_322:
	s_add_i32 s56, 0, 0x10000
	s_add_i32 vcc_lo, 0, 0x14000
	s_waitcnt lgkmcnt(0)
	ds_read_b128 v[154:157], v246
	ds_read_b128 v[164:167], v246 offset:1024
	ds_read_b128 v[168:171], v246 offset:2048
	ds_read_b128 v[172:175], v246 offset:3072
	ds_read_b128 v[176:179], v246 offset:16384
	ds_read_b128 v[180:183], v246 offset:17408
	ds_read_b128 v[184:187], v246 offset:18432
	ds_read_b128 v[188:191], v246 offset:19456
	s_add_i32 m0, s89, 0xc000
	ds_read_b128 v[192:195], v145
	ds_read_b128 v[196:199], v145 offset:1024
	ds_read_b128 v[222:225], v145 offset:2048
	ds_read_b128 v[226:229], v145 offset:3072
	ds_read_b128 v[230:233], v145 offset:4096
	ds_read_b128 v[234:237], v145 offset:5120
	ds_read_b128 v[238:241], v145 offset:6144
	ds_read_b128 v[242:245], v145 offset:7168
	global_load_lds_dwordx4 v150, s[14:15]
	s_add_i32 m0, s89, 0xe000
	s_nop 0
	global_load_lds_dwordx4 v152, s[14:15]
	s_add_u32 s4, s14, 0xfff80080
	s_addc_u32 s5, s15, -1
	s_cmp_eq_u32 s55, 28
	s_cselect_b32 s53, s1, s5
	s_cselect_b32 s52, s28, s4
	s_cselect_b32 s5, s29, s54
	s_cselect_b32 s4, s43, s45
	s_waitcnt vmcnt(8)
	s_waitcnt lgkmcnt(0)
	s_barrier
; #define PG8_STAGE(bufoff, gbase, voff) do { _Pragma("unroll") for (int _i = 0; _i < 2; ++_i) \
;         __builtin_amdgcn_global_load_lds((const unsigned*)((const char*)(gbase) + (voff)[_i]), (PG8_LAS unsigned*)(lds + (bufoff) + ldsw + _i * 8192), 16, 0, 0); } while (0)
; #define PG8_LDA(dst, b, h) do { _Pragma("unroll") for (int m = 0; m < 4; ++m) _Pragma("unroll") for (int k = 0; k < 2; ++k) dst[m][k] = *(const PG8_LAS bf16x8*)(lds + PG8_SA(b, h) + aoff + m * 2048 + k * 1024); } while (0)
; #define PG8_MMA(ai, bj, At, Bt) do { __builtin_amdgcn_s_setprio(1); _Pragma("unroll") for (int m = 0; m < 4; ++m) _Pragma("unroll") for (int n = 0; n < 2; ++n) _Pragma("unroll") for (int k = 0; k < 2; ++k) \
;         acc[ai][bj][m][n] = __builtin_amdgcn_mfma_f32_16x16x32_bf16(Bt[n][k], At[m][k], acc[ai][bj][m][n], 0, 0, 0); __builtin_amdgcn_s_setprio(0); } while (0)
; #define PG8_WAIT_V(n) asm volatile("s_waitcnt vmcnt(" #n ")" ::: "memory")
; #define PG8_WAIT_L(n) asm volatile("s_waitcnt lgkmcnt(" #n ")" ::: "memory")
; #define PG8_BAR __builtin_amdgcn_s_barrier()
; #define PG8_SCHED __builtin_amdgcn_sched_barrier(0)
; template <class Epi, class Sched, bool ALIGN_EPI = false, bool SP2 = false>
; __device__ __forceinline__ void gemm_phase(PG8_LAS unsigned char* lds, const Gemm g, const Sched& S, const Epi& E) {
;     ...
;             PG8_WAIT_V(8); PG8_WAIT_L(0); PG8_BAR; PG8_MMA(0, 0, At, B0); PG8_MMA(0, 1, At, B1); PG8_BAR; PG8_SCHED;
;             PG8_LDA(At, 0, 1); PG8_STAGE(PG8_SB(0, 0), b2, voffB); PG8_STAGE(PG8_SB(0, 1), b2 + hstep, voffB); PG8_STAGE(PG8_SA(0, 0), a2, voffA);
;             PG8_WAIT_V(8); PG8_WAIT_L(0); PG8_BAR; PG8_MMA(1, 0, At, B0); PG8_MMA(1, 1, At, B1); PG8_BAR; PG8_SCHED;
	s_setprio 1
	s_waitcnt lgkmcnt(0)
	v_mfma_f32_16x16x32_bf16 v[124:127], v[154:157], v[192:195], v[124:127]
	v_mfma_f32_16x16x32_bf16 v[120:123], v[168:171], v[192:195], v[120:123]
	v_mfma_f32_16x16x32_bf16 v[116:119], v[154:157], v[222:225], v[116:119]
	v_mfma_f32_16x16x32_bf16 v[112:115], v[168:171], v[222:225], v[112:115]
	v_mfma_f32_16x16x32_bf16 v[108:111], v[154:157], v[230:233], v[108:111]
	v_mfma_f32_16x16x32_bf16 v[104:107], v[168:171], v[230:233], v[104:107]
	v_mfma_f32_16x16x32_bf16 v[100:103], v[154:157], v[238:241], v[100:103]
	v_mfma_f32_16x16x32_bf16 v[96:99], v[168:171], v[238:241], v[96:99]
	v_mfma_f32_16x16x32_bf16 v[124:127], v[164:167], v[196:199], v[124:127]
	v_mfma_f32_16x16x32_bf16 v[120:123], v[172:175], v[196:199], v[120:123]
	v_mfma_f32_16x16x32_bf16 v[116:119], v[164:167], v[226:229], v[116:119]
	v_mfma_f32_16x16x32_bf16 v[112:115], v[172:175], v[226:229], v[112:115]
	v_mfma_f32_16x16x32_bf16 v[108:111], v[164:167], v[234:237], v[108:111]
	v_mfma_f32_16x16x32_bf16 v[104:107], v[172:175], v[234:237], v[104:107]
	v_mfma_f32_16x16x32_bf16 v[100:103], v[164:167], v[242:245], v[100:103]
	v_mfma_f32_16x16x32_bf16 v[96:99], v[172:175], v[242:245], v[96:99]
	s_setprio 0
	s_setprio 1
	v_mfma_f32_16x16x32_bf16 v[92:95], v[176:179], v[192:195], v[92:95]
	v_mfma_f32_16x16x32_bf16 v[88:91], v[184:187], v[192:195], v[88:91]
	v_mfma_f32_16x16x32_bf16 v[84:87], v[176:179], v[222:225], v[84:87]
	v_mfma_f32_16x16x32_bf16 v[80:83], v[184:187], v[222:225], v[80:83]
	v_mfma_f32_16x16x32_bf16 v[76:79], v[176:179], v[230:233], v[76:79]
	v_mfma_f32_16x16x32_bf16 v[72:75], v[184:187], v[230:233], v[72:75]
	v_mfma_f32_16x16x32_bf16 v[68:71], v[176:179], v[238:241], v[68:71]
	v_mfma_f32_16x16x32_bf16 v[64:67], v[184:187], v[238:241], v[64:67]
	v_mfma_f32_16x16x32_bf16 v[92:95], v[180:183], v[196:199], v[92:95]
	v_mfma_f32_16x16x32_bf16 v[88:91], v[188:191], v[196:199], v[88:91]
	v_mfma_f32_16x16x32_bf16 v[84:87], v[180:183], v[226:229], v[84:87]
	v_mfma_f32_16x16x32_bf16 v[80:83], v[188:191], v[226:229], v[80:83]
	v_mfma_f32_16x16x32_bf16 v[76:79], v[180:183], v[234:237], v[76:79]
	v_mfma_f32_16x16x32_bf16 v[72:75], v[188:191], v[234:237], v[72:75]
	v_mfma_f32_16x16x32_bf16 v[68:71], v[180:183], v[242:245], v[68:71]
	v_mfma_f32_16x16x32_bf16 v[64:67], v[188:191], v[242:245], v[64:67]
	s_setprio 0
	s_barrier
	s_add_i32 s56, s56, s63
	s_mov_b32 m0, s56
	ds_read_b128 v[192:195], v145 offset:16384
	ds_read_b128 v[196:199], v145 offset:17408
	ds_read_b128 v[222:225], v145 offset:18432
	ds_read_b128 v[226:229], v145 offset:19456
	ds_read_b128 v[230:233], v145 offset:20480
	ds_read_b128 v[234:237], v145 offset:21504
	ds_read_b128 v[238:241], v145 offset:22528
	ds_read_b128 v[242:245], v145 offset:23552
	global_load_lds_dwordx4 v130, s[4:5]
	s_add_i32 m0, s56, 0x2000
	s_add_u32 s56, s4, 0x80000
	s_addc_u32 s57, s5, 0
	s_add_i32 vcc_lo, vcc_lo, s63
	global_load_lds_dwordx4 v134, s[4:5]
	s_mov_b32 m0, vcc_lo
	s_nop 0
	global_load_lds_dwordx4 v130, s[56:57]
	s_add_i32 m0, vcc_lo, 0x2000
	s_nop 0
	global_load_lds_dwordx4 v134, s[56:57]
	s_mov_b32 m0, s89
	s_nop 0
	global_load_lds_dwordx4 v128, s[52:53]
	s_mov_b32 m0, s91
	s_nop 0
	global_load_lds_dwordx4 v132, s[52:53]
	s_add_u32 s98, s52, 0x80
	s_addc_u32 s99, s53, 0
	s_waitcnt vmcnt(8)
	s_waitcnt lgkmcnt(0)
	s_barrier
	s_setprio 1
	s_waitcnt lgkmcnt(0)
	v_mfma_f32_16x16x32_bf16 v[60:63], v[154:157], v[192:195], v[60:63]
	v_mfma_f32_16x16x32_bf16 v[56:59], v[168:171], v[192:195], v[56:59]
	v_mfma_f32_16x16x32_bf16 v[52:55], v[154:157], v[222:225], v[52:55]
	v_mfma_f32_16x16x32_bf16 v[48:51], v[168:171], v[222:225], v[48:51]
	v_mfma_f32_16x16x32_bf16 v[44:47], v[154:157], v[230:233], v[44:47]
	v_mfma_f32_16x16x32_bf16 v[40:43], v[168:171], v[230:233], v[40:43]
	v_mfma_f32_16x16x32_bf16 v[36:39], v[154:157], v[238:241], v[36:39]
	v_mfma_f32_16x16x32_bf16 v[32:35], v[168:171], v[238:241], v[32:35]
	v_mfma_f32_16x16x32_bf16 v[60:63], v[164:167], v[196:199], v[60:63]
	v_mfma_f32_16x16x32_bf16 v[56:59], v[172:175], v[196:199], v[56:59]
	v_mfma_f32_16x16x32_bf16 v[52:55], v[164:167], v[226:229], v[52:55]
	v_mfma_f32_16x16x32_bf16 v[48:51], v[172:175], v[226:229], v[48:51]
	v_mfma_f32_16x16x32_bf16 v[44:47], v[164:167], v[234:237], v[44:47]
	v_mfma_f32_16x16x32_bf16 v[40:43], v[172:175], v[234:237], v[40:43]
	v_mfma_f32_16x16x32_bf16 v[36:39], v[164:167], v[242:245], v[36:39]
	v_mfma_f32_16x16x32_bf16 v[32:35], v[172:175], v[242:245], v[32:35]
	s_setprio 0
	s_setprio 1
	v_mfma_f32_16x16x32_bf16 v[28:31], v[176:179], v[192:195], v[28:31]
	v_mfma_f32_16x16x32_bf16 v[24:27], v[184:187], v[192:195], v[24:27]
	v_mfma_f32_16x16x32_bf16 v[20:23], v[176:179], v[222:225], v[20:23]
	v_mfma_f32_16x16x32_bf16 v[16:19], v[184:187], v[222:225], v[16:19]
	v_mfma_f32_16x16x32_bf16 v[12:15], v[176:179], v[230:233], v[12:15]
	v_mfma_f32_16x16x32_bf16 v[8:11], v[184:187], v[230:233], v[8:11]
	v_mfma_f32_16x16x32_bf16 v[4:7], v[176:179], v[238:241], v[4:7]
	v_mfma_f32_16x16x32_bf16 v[0:3], v[184:187], v[238:241], v[0:3]
	v_mfma_f32_16x16x32_bf16 v[28:31], v[180:183], v[196:199], v[28:31]
	v_mfma_f32_16x16x32_bf16 v[24:27], v[188:191], v[196:199], v[24:27]
	v_mfma_f32_16x16x32_bf16 v[20:23], v[180:183], v[226:229], v[20:23]
	v_mfma_f32_16x16x32_bf16 v[16:19], v[188:191], v[226:229], v[16:19]
	v_mfma_f32_16x16x32_bf16 v[12:15], v[180:183], v[234:237], v[12:15]
	v_mfma_f32_16x16x32_bf16 v[8:11], v[188:191], v[234:237], v[8:11]
	v_mfma_f32_16x16x32_bf16 v[4:7], v[180:183], v[242:245], v[4:7]
	v_mfma_f32_16x16x32_bf16 v[0:3], v[188:191], v[242:245], v[0:3]
	s_setprio 0
	s_barrier
; #define PG8_STAGE(bufoff, gbase, voff) do { _Pragma("unroll") for (int _i = 0; _i < 2; ++_i) \
;         __builtin_amdgcn_global_load_lds((const unsigned*)((const char*)(gbase) + (voff)[_i]), (PG8_LAS unsigned*)(lds + (bufoff) + ldsw + _i * 8192), 16, 0, 0); } while (0)
; #define PG8_LDA(dst, b, h) do { _Pragma("unroll") for (int m = 0; m < 4; ++m) _Pragma("unroll") for (int k = 0; k < 2; ++k) dst[m][k] = *(const PG8_LAS bf16x8*)(lds + PG8_SA(b, h) + aoff + m * 2048 + k * 1024); } while (0)
; #define PG8_LDB(dst, b, h) do { _Pragma("unroll") for (int n = 0; n < 2; ++n) _Pragma("unroll") for (int k = 0; k < 2; ++k) dst[n][k] = *(const PG8_LAS bf16x8*)(lds + PG8_SB(b, h) + boff + n * 2048 + k * 1024); } while (0)
; #define PG8_MMA(ai, bj, At, Bt) do { __builtin_amdgcn_s_setprio(1); _Pragma("unroll") for (int m = 0; m < 4; ++m) _Pragma("unroll") for (int n = 0; n < 2; ++n) _Pragma("unroll") for (int k = 0; k < 2; ++k) \
;         acc[ai][bj][m][n] = __builtin_amdgcn_mfma_f32_16x16x32_bf16(Bt[n][k], At[m][k], acc[ai][bj][m][n], 0, 0, 0); __builtin_amdgcn_s_setprio(0); } while (0)
; #define PG8_WAIT_V(n) asm volatile("s_waitcnt vmcnt(" #n ")" ::: "memory")
; #define PG8_WAIT_L(n) asm volatile("s_waitcnt lgkmcnt(" #n ")" ::: "memory")
; #define PG8_BAR __builtin_amdgcn_s_barrier()
; #define PG8_SCHED __builtin_amdgcn_sched_barrier(0)
; template <class Epi, class Sched, bool ALIGN_EPI = false, bool SP2 = false>
; __device__ __forceinline__ void gemm_phase(PG8_LAS unsigned char* lds, const Gemm g, const Sched& S, const Epi& E) {
;     ...
;             PG8_LDB(B0, 1, 0); PG8_LDB(B1, 1, 1); PG8_SCHED; PG8_LDA(At, 1, 0); PG8_STAGE(PG8_SA(0, 1), a2 + hstep, voffA);
;             PG8_WAIT_V(8); PG8_WAIT_L(0); PG8_BAR; PG8_MMA(0, 0, At, B0); PG8_MMA(0, 1, At, B1); PG8_BAR; PG8_SCHED;
;             PG8_LDA(At, 1, 1); PG8_STAGE(PG8_SB(1, 0), b3, voffB); PG8_STAGE(PG8_SB(1, 1), b3 + hstep, voffB); PG8_STAGE(PG8_SA(1, 0), a3, voffA);
;             PG8_WAIT_V(8); PG8_WAIT_L(0); PG8_BAR; PG8_MMA(1, 0, At, B0); PG8_MMA(1, 1, At, B1); PG8_BAR; PG8_SCHED;
	s_add_i32 s56, 0, 0x18000
	s_add_i32 s57, 0, 0x1c000
	ds_read_b128 v[154:157], v246 offset:32768
	ds_read_b128 v[164:167], v246 offset:33792
	ds_read_b128 v[168:171], v246 offset:34816
	ds_read_b128 v[172:175], v246 offset:35840
	ds_read_b128 v[176:179], v246 offset:49152
	ds_read_b128 v[180:183], v246 offset:50176
	ds_read_b128 v[184:187], v246 offset:51200
	ds_read_b128 v[188:191], v246 offset:52224
	s_add_u32 s52, s52, 0x80000
	s_addc_u32 s53, s53, 0
	s_mov_b32 m0, s12
	ds_read_b128 v[192:195], v145 offset:32768
	ds_read_b128 v[196:199], v145 offset:33792
	ds_read_b128 v[222:225], v145 offset:34816
	ds_read_b128 v[226:229], v145 offset:35840
	ds_read_b128 v[230:233], v145 offset:36864
	ds_read_b128 v[234:237], v145 offset:37888
	ds_read_b128 v[238:241], v145 offset:38912
	ds_read_b128 v[242:245], v145 offset:39936
	global_load_lds_dwordx4 v128, s[52:53]
	s_mov_b32 m0, s13
	s_nop 0
	global_load_lds_dwordx4 v132, s[52:53]
	s_waitcnt vmcnt(8)
	s_waitcnt lgkmcnt(0)
	s_barrier
	s_setprio 1
	s_waitcnt lgkmcnt(0)
	v_mfma_f32_16x16x32_bf16 v[124:127], v[154:157], v[192:195], v[124:127]
	v_mfma_f32_16x16x32_bf16 v[120:123], v[168:171], v[192:195], v[120:123]
	v_mfma_f32_16x16x32_bf16 v[116:119], v[154:157], v[222:225], v[116:119]
	v_mfma_f32_16x16x32_bf16 v[112:115], v[168:171], v[222:225], v[112:115]
	v_mfma_f32_16x16x32_bf16 v[108:111], v[154:157], v[230:233], v[108:111]
	v_mfma_f32_16x16x32_bf16 v[104:107], v[168:171], v[230:233], v[104:107]
	v_mfma_f32_16x16x32_bf16 v[100:103], v[154:157], v[238:241], v[100:103]
	v_mfma_f32_16x16x32_bf16 v[96:99], v[168:171], v[238:241], v[96:99]
	v_mfma_f32_16x16x32_bf16 v[124:127], v[164:167], v[196:199], v[124:127]
	v_mfma_f32_16x16x32_bf16 v[120:123], v[172:175], v[196:199], v[120:123]
	v_mfma_f32_16x16x32_bf16 v[116:119], v[164:167], v[226:229], v[116:119]
	v_mfma_f32_16x16x32_bf16 v[112:115], v[172:175], v[226:229], v[112:115]
	v_mfma_f32_16x16x32_bf16 v[108:111], v[164:167], v[234:237], v[108:111]
	v_mfma_f32_16x16x32_bf16 v[104:107], v[172:175], v[234:237], v[104:107]
	v_mfma_f32_16x16x32_bf16 v[100:103], v[164:167], v[242:245], v[100:103]
	v_mfma_f32_16x16x32_bf16 v[96:99], v[172:175], v[242:245], v[96:99]
	s_setprio 0
	s_setprio 1
	v_mfma_f32_16x16x32_bf16 v[92:95], v[176:179], v[192:195], v[92:95]
	v_mfma_f32_16x16x32_bf16 v[88:91], v[184:187], v[192:195], v[88:91]
	v_mfma_f32_16x16x32_bf16 v[84:87], v[176:179], v[222:225], v[84:87]
	v_mfma_f32_16x16x32_bf16 v[80:83], v[184:187], v[222:225], v[80:83]
	v_mfma_f32_16x16x32_bf16 v[76:79], v[176:179], v[230:233], v[76:79]
	v_mfma_f32_16x16x32_bf16 v[72:75], v[184:187], v[230:233], v[72:75]
	v_mfma_f32_16x16x32_bf16 v[68:71], v[176:179], v[238:241], v[68:71]
	v_mfma_f32_16x16x32_bf16 v[64:67], v[184:187], v[238:241], v[64:67]
	v_mfma_f32_16x16x32_bf16 v[92:95], v[180:183], v[196:199], v[92:95]
	v_mfma_f32_16x16x32_bf16 v[88:91], v[188:191], v[196:199], v[88:91]
	v_mfma_f32_16x16x32_bf16 v[84:87], v[180:183], v[226:229], v[84:87]
	v_mfma_f32_16x16x32_bf16 v[80:83], v[188:191], v[226:229], v[80:83]
	v_mfma_f32_16x16x32_bf16 v[76:79], v[180:183], v[234:237], v[76:79]
	v_mfma_f32_16x16x32_bf16 v[72:75], v[188:191], v[234:237], v[72:75]
	v_mfma_f32_16x16x32_bf16 v[68:71], v[180:183], v[242:245], v[68:71]
	v_mfma_f32_16x16x32_bf16 v[64:67], v[188:191], v[242:245], v[64:67]
	s_setprio 0
	s_barrier
	s_add_i32 s52, s56, s63
	s_mov_b32 m0, s52
	ds_read_b128 v[192:195], v145 offset:49152
	ds_read_b128 v[196:199], v145 offset:50176
	ds_read_b128 v[222:225], v145 offset:51200
	ds_read_b128 v[226:229], v145 offset:52224
	ds_read_b128 v[230:233], v145 offset:53248
	ds_read_b128 v[234:237], v145 offset:54272
	ds_read_b128 v[238:241], v145 offset:55296
	ds_read_b128 v[242:245], v145 offset:56320
	s_add_u32 s4, s4, 0x80
	s_addc_u32 s5, s5, 0
	global_load_lds_dwordx4 v130, s[4:5]
	s_add_i32 m0, s52, 0x2000
	s_add_i32 s52, s57, s63
	global_load_lds_dwordx4 v134, s[4:5]
	s_add_u32 s4, s4, 0x80000
	s_addc_u32 s5, s5, 0
	s_mov_b32 m0, s52
	s_nop 0
	global_load_lds_dwordx4 v130, s[4:5]
	s_add_i32 m0, s52, 0x2000
	s_nop 0
	global_load_lds_dwordx4 v134, s[4:5]
	s_mov_b32 m0, s78
	s_nop 0
	global_load_lds_dwordx4 v128, s[98:99]
	s_mov_b32 m0, s79
	s_nop 0
	global_load_lds_dwordx4 v132, s[98:99]
	s_waitcnt vmcnt(8)
	s_waitcnt lgkmcnt(0)
	s_barrier
	s_setprio 1
	s_waitcnt lgkmcnt(0)
	v_mfma_f32_16x16x32_bf16 v[60:63], v[154:157], v[192:195], v[60:63]
	v_mfma_f32_16x16x32_bf16 v[56:59], v[168:171], v[192:195], v[56:59]
	v_mfma_f32_16x16x32_bf16 v[52:55], v[154:157], v[222:225], v[52:55]
	v_mfma_f32_16x16x32_bf16 v[48:51], v[168:171], v[222:225], v[48:51]
	v_mfma_f32_16x16x32_bf16 v[44:47], v[154:157], v[230:233], v[44:47]
	v_mfma_f32_16x16x32_bf16 v[40:43], v[168:171], v[230:233], v[40:43]
	v_mfma_f32_16x16x32_bf16 v[36:39], v[154:157], v[238:241], v[36:39]
	v_mfma_f32_16x16x32_bf16 v[32:35], v[168:171], v[238:241], v[32:35]
	v_mfma_f32_16x16x32_bf16 v[60:63], v[164:167], v[196:199], v[60:63]
	v_mfma_f32_16x16x32_bf16 v[56:59], v[172:175], v[196:199], v[56:59]
	v_mfma_f32_16x16x32_bf16 v[52:55], v[164:167], v[226:229], v[52:55]
	v_mfma_f32_16x16x32_bf16 v[48:51], v[172:175], v[226:229], v[48:51]
	v_mfma_f32_16x16x32_bf16 v[44:47], v[164:167], v[234:237], v[44:47]
	v_mfma_f32_16x16x32_bf16 v[40:43], v[172:175], v[234:237], v[40:43]
	v_mfma_f32_16x16x32_bf16 v[36:39], v[164:167], v[242:245], v[36:39]
	v_mfma_f32_16x16x32_bf16 v[32:35], v[172:175], v[242:245], v[32:35]
	s_setprio 0
	s_setprio 1
	v_mfma_f32_16x16x32_bf16 v[28:31], v[176:179], v[192:195], v[28:31]
	v_mfma_f32_16x16x32_bf16 v[24:27], v[184:187], v[192:195], v[24:27]
	v_mfma_f32_16x16x32_bf16 v[20:23], v[176:179], v[222:225], v[20:23]
	v_mfma_f32_16x16x32_bf16 v[16:19], v[184:187], v[222:225], v[16:19]
	v_mfma_f32_16x16x32_bf16 v[12:15], v[176:179], v[230:233], v[12:15]
	v_mfma_f32_16x16x32_bf16 v[8:11], v[184:187], v[230:233], v[8:11]
	v_mfma_f32_16x16x32_bf16 v[4:7], v[176:179], v[238:241], v[4:7]
	v_mfma_f32_16x16x32_bf16 v[0:3], v[184:187], v[238:241], v[0:3]
	v_mfma_f32_16x16x32_bf16 v[28:31], v[180:183], v[196:199], v[28:31]
	v_mfma_f32_16x16x32_bf16 v[24:27], v[188:191], v[196:199], v[24:27]
	v_mfma_f32_16x16x32_bf16 v[20:23], v[180:183], v[226:229], v[20:23]
	v_mfma_f32_16x16x32_bf16 v[16:19], v[188:191], v[226:229], v[16:19]
	v_mfma_f32_16x16x32_bf16 v[12:15], v[180:183], v[234:237], v[12:15]
	v_mfma_f32_16x16x32_bf16 v[8:11], v[188:191], v[234:237], v[8:11]
	v_mfma_f32_16x16x32_bf16 v[4:7], v[180:183], v[242:245], v[4:7]
	v_mfma_f32_16x16x32_bf16 v[0:3], v[188:191], v[242:245], v[0:3]
	s_setprio 0
	s_barrier
	s_add_i32 s55, s55, 2
	s_add_u32 s14, s14, 0x100
	s_addc_u32 s15, s15, 0
	s_add_u32 s45, s45, 0x100
	s_addc_u32 s54, s54, 0
	s_cmp_gt_u32 s55, 29
	s_cbranch_scc0 .LBB0_322
	s_and_b64 vcc, exec, s[82:83]
	s_cbranch_vccz .LBB0_325
	s_barrier

;     __host__ __device__ bool next(int i, Unit& u) const { if (!base.next(i >> 1, u)) return false; if (i & 1) { u.pm += 64; u.pn += 8; } return true; }
; #define PG8_STAGE(bufoff, gbase, voff) do { _Pragma("unroll") for (int _i = 0; _i < 2; ++_i) \
;         __builtin_amdgcn_global_load_lds((const unsigned*)((const char*)(gbase) + (voff)[_i]), (PG8_LAS unsigned*)(lds + (bufoff) + ldsw + _i * 8192), 16, 0, 0); } while (0)
; #define PG8_LDA(dst, b, h) do { _Pragma("unroll") for (int m = 0; m < 4; ++m) _Pragma("unroll") for (int k = 0; k < 2; ++k) dst[m][k] = *(const PG8_LAS bf16x8*)(lds + PG8_SA(b, h) + aoff + m * 2048 + k * 1024); } while (0)
; #define PG8_LDB(dst, b, h) do { _Pragma("unroll") for (int n = 0; n < 2; ++n) _Pragma("unroll") for (int k = 0; k < 2; ++k) dst[n][k] = *(const PG8_LAS bf16x8*)(lds + PG8_SB(b, h) + boff + n * 2048 + k * 1024); } while (0)
; #define PG8_WAIT_V(n) asm volatile("s_waitcnt vmcnt(" #n ")" ::: "memory")
; #define PG8_BAR __builtin_amdgcn_s_barrier()
; template <class Epi, class Sched, bool ALIGN_EPI = false, bool SP2 = false>
; __device__ __forceinline__ void gemm_phase(PG8_LAS unsigned char* lds, const Gemm g, const Sched& S, const Epi& E) {
;     ...
;         const bool has_next = S.next(ui + 1, nxt);
;         const char* nA = has_next ? (const char*)g.A + (size_t)nxt.pm * tstep : cA; const char* nB = has_next ? (const char*)g.Bt + (size_t)nxt.pn * tstep : cB;
;         for (int t = 0; t < nt; t += 2) {
;             const bool last = (t == nt - 2);
;             const char* a1 = cA + (size_t)(t + 1) * kstep;
;             const char* a2 = last ? nA : cA + (size_t)(t + 2) * kstep; const char* b2 = last ? nB : cB + (size_t)(t + 2) * kstep;
;             const char* a3 = a2 + kstep; const char* b3 = b2 + kstep;
;             if (last && has_next) S.a_ready(nxt);
;             if constexpr (SP2) {
;             PG8_LDB(B0, 0, 0); PG8_LDB(B1, 0, 1); PG8_SCHED; PG8_LDA(At, 0, 0); PG8_STAGE(PG8_SA(1, 1), a1 + hstep, voffA);
;             PG8_WAIT_V(8); PG8_WAIT_L(0); PG8_BAR; PG8_MMA(0, 0, At, B0); PG8_MMA(0, 1, At, B1); PG8_BAR; PG8_SCHED;
;     ...
;         for (int a = 0; a < 2; ++a)
; #pragma unroll
;             for (int b = 0; b < 2; ++b)
; #pragma unroll
;                 for (int m = 0; m < 4; ++m)
; #pragma unroll
;                     for (int n = 0; n < 2; ++n) acc[a][b][m][n] = (f32x4){0.f, 0.f, 0.f, 0.f};
.LBB0_848:
	s_ashr_i32 s11, s10, 31
	s_lshl_b64 s[42:43], s[10:11], 20
	s_add_u32 s42, s66, s42
	s_addc_u32 s43, s67, s43
	s_and_b64 s[44:45], s[14:15], exec
	s_cselect_b32 s11, s43, s53
	s_cselect_b32 s63, s42, s52
	s_ashr_i32 s13, s12, 31
	s_lshl_b64 s[44:45], s[12:13], 20
	s_add_u32 s44, s0, s44
	s_addc_u32 s45, s1, s45
	s_and_b64 s[70:71], s[14:15], exec
	s_cselect_b32 s13, s45, s5
	s_cselect_b32 s72, s44, s4
	s_add_u32 s70, s52, 0x80080
	s_addc_u32 s71, s53, 0
	s_add_u32 s73, s4, 0x100
	v_mov_b32_e32 v0, 0
	s_addc_u32 s74, s5, 0
	s_mov_b32 s75, -2
	v_add_u32_e32 v200, 0x10000, v141
	v_mov_b32_e32 v1, v0
	v_mov_b32_e32 v2, v0
	v_mov_b32_e32 v3, v0
	v_mov_b32_e32 v8, v0
	v_mov_b32_e32 v9, v0
	v_mov_b32_e32 v10, v0
	v_mov_b32_e32 v11, v0
	v_mov_b32_e32 v16, v0
	v_mov_b32_e32 v17, v0
	v_mov_b32_e32 v18, v0
	v_mov_b32_e32 v19, v0
	v_mov_b32_e32 v24, v0
	v_mov_b32_e32 v25, v0
	v_mov_b32_e32 v26, v0
	v_mov_b32_e32 v27, v0
	v_mov_b32_e32 v32, v0
	v_mov_b32_e32 v33, v0
	v_mov_b32_e32 v34, v0
	v_mov_b32_e32 v35, v0
	v_mov_b32_e32 v40, v0
	v_mov_b32_e32 v41, v0
	v_mov_b32_e32 v42, v0
	v_mov_b32_e32 v43, v0
	v_mov_b32_e32 v48, v0
	v_mov_b32_e32 v49, v0
	v_mov_b32_e32 v50, v0
	v_mov_b32_e32 v51, v0
	v_mov_b32_e32 v56, v0
	v_mov_b32_e32 v57, v0
	v_mov_b32_e32 v58, v0
	v_mov_b32_e32 v59, v0
	v_mov_b32_e32 v4, v0
	v_mov_b32_e32 v5, v0
	v_mov_b32_e32 v6, v0
	v_mov_b32_e32 v7, v0
	v_mov_b32_e32 v12, v0
	v_mov_b32_e32 v13, v0
	v_mov_b32_e32 v14, v0
	v_mov_b32_e32 v15, v0
	v_mov_b32_e32 v20, v0
	v_mov_b32_e32 v21, v0
	v_mov_b32_e32 v22, v0
	v_mov_b32_e32 v23, v0
	v_mov_b32_e32 v28, v0
	v_mov_b32_e32 v29, v0
	v_mov_b32_e32 v30, v0
	v_mov_b32_e32 v31, v0
	v_mov_b32_e32 v36, v0
	v_mov_b32_e32 v37, v0
	v_mov_b32_e32 v38, v0
	v_mov_b32_e32 v39, v0
	v_mov_b32_e32 v44, v0
	v_mov_b32_e32 v45, v0
	v_mov_b32_e32 v46, v0
	v_mov_b32_e32 v47, v0
	v_mov_b32_e32 v52, v0
	v_mov_b32_e32 v53, v0
	v_mov_b32_e32 v54, v0
	v_mov_b32_e32 v55, v0
	v_mov_b32_e32 v60, v0
	v_mov_b32_e32 v61, v0
	v_mov_b32_e32 v62, v0
	v_mov_b32_e32 v63, v0
	v_mov_b32_e32 v64, v0
	v_mov_b32_e32 v65, v0
	v_mov_b32_e32 v66, v0
	v_mov_b32_e32 v67, v0
	v_mov_b32_e32 v72, v0
	v_mov_b32_e32 v73, v0
	v_mov_b32_e32 v74, v0
	v_mov_b32_e32 v75, v0
	v_mov_b32_e32 v80, v0
	v_mov_b32_e32 v81, v0
	v_mov_b32_e32 v82, v0
	v_mov_b32_e32 v83, v0
	v_mov_b32_e32 v88, v0
	v_mov_b32_e32 v89, v0
	v_mov_b32_e32 v90, v0
	v_mov_b32_e32 v91, v0
	v_mov_b32_e32 v96, v0
	v_mov_b32_e32 v97, v0
	v_mov_b32_e32 v98, v0
	v_mov_b32_e32 v99, v0
	v_mov_b32_e32 v104, v0
	v_mov_b32_e32 v105, v0
	v_mov_b32_e32 v106, v0
	v_mov_b32_e32 v107, v0
	v_mov_b32_e32 v112, v0
	v_mov_b32_e32 v113, v0
	v_mov_b32_e32 v114, v0
	v_mov_b32_e32 v115, v0
	v_mov_b32_e32 v120, v0
	v_mov_b32_e32 v121, v0
	v_mov_b32_e32 v122, v0
	v_mov_b32_e32 v123, v0
	v_mov_b32_e32 v68, v0
	v_mov_b32_e32 v69, v0
	v_mov_b32_e32 v70, v0
	v_mov_b32_e32 v71, v0
	v_mov_b32_e32 v76, v0
	v_mov_b32_e32 v77, v0
	v_mov_b32_e32 v78, v0
	v_mov_b32_e32 v79, v0
	v_mov_b32_e32 v84, v0
	v_mov_b32_e32 v85, v0
	v_mov_b32_e32 v86, v0
	v_mov_b32_e32 v87, v0
	v_mov_b32_e32 v92, v0
	v_mov_b32_e32 v93, v0
	v_mov_b32_e32 v94, v0
	v_mov_b32_e32 v95, v0
	v_mov_b32_e32 v100, v0
	v_mov_b32_e32 v101, v0
	v_mov_b32_e32 v102, v0
	v_mov_b32_e32 v103, v0
	v_mov_b32_e32 v108, v0
	v_mov_b32_e32 v109, v0
	v_mov_b32_e32 v110, v0
	v_mov_b32_e32 v111, v0
	v_mov_b32_e32 v116, v0
	v_mov_b32_e32 v117, v0
	v_mov_b32_e32 v118, v0
	v_mov_b32_e32 v119, v0
	v_mov_b32_e32 v124, v0
	v_mov_b32_e32 v125, v0
	v_mov_b32_e32 v126, v0
	v_mov_b32_e32 v127, v0
.LBB0_849:
	s_add_i32 s76, 0, 0x10000
	s_add_i32 s78, 0, 0x14000
	ds_read_b128 v[144:147], v200
	ds_read_b128 v[148:151], v200 offset:1024
	ds_read_b128 v[152:155], v200 offset:2048
	ds_read_b128 v[156:159], v200 offset:3072
	ds_read_b128 v[164:167], v200 offset:16384
	ds_read_b128 v[168:171], v200 offset:17408
	ds_read_b128 v[172:175], v200 offset:18432
	ds_read_b128 v[176:179], v200 offset:19456
	s_add_i32 m0, s51, 0xc000
	ds_read_b128 v[180:183], v143
	ds_read_b128 v[184:187], v143 offset:1024
	ds_read_b128 v[188:191], v143 offset:2048
	ds_read_b128 v[192:195], v143 offset:3072
	ds_read_b128 v[196:199], v143 offset:4096
	ds_read_b128 v[222:225], v143 offset:5120
	ds_read_b128 v[226:229], v143 offset:6144
	ds_read_b128 v[230:233], v143 offset:7168
	global_load_lds_dwordx4 v134, s[70:71]
	s_add_i32 m0, s51, 0xe000
	s_nop 0
	global_load_lds_dwordx4 v136, s[70:71]
	s_add_u32 s4, s70, 0xfff80080
	s_addc_u32 s5, s71, -1
	s_cmp_eq_u32 s75, 28
	s_cselect_b32 s53, s11, s5
	s_cselect_b32 s52, s63, s4
	s_cselect_b32 s5, s13, s74
	s_cselect_b32 s4, s72, s73
	s_waitcnt vmcnt(8)
	s_waitcnt lgkmcnt(0)
	s_barrier
; #define PG8_STAGE(bufoff, gbase, voff) do { _Pragma("unroll") for (int _i = 0; _i < 2; ++_i) \
;         __builtin_amdgcn_global_load_lds((const unsigned*)((const char*)(gbase) + (voff)[_i]), (PG8_LAS unsigned*)(lds + (bufoff) + ldsw + _i * 8192), 16, 0, 0); } while (0)
; #define PG8_LDA(dst, b, h) do { _Pragma("unroll") for (int m = 0; m < 4; ++m) _Pragma("unroll") for (int k = 0; k < 2; ++k) dst[m][k] = *(const PG8_LAS bf16x8*)(lds + PG8_SA(b, h) + aoff + m * 2048 + k * 1024); } while (0)
; #define PG8_MMA(ai, bj, At, Bt) do { __builtin_amdgcn_s_setprio(1); _Pragma("unroll") for (int m = 0; m < 4; ++m) _Pragma("unroll") for (int n = 0; n < 2; ++n) _Pragma("unroll") for (int k = 0; k < 2; ++k) \
;         acc[ai][bj][m][n] = __builtin_amdgcn_mfma_f32_16x16x32_bf16(Bt[n][k], At[m][k], acc[ai][bj][m][n], 0, 0, 0); __builtin_amdgcn_s_setprio(0); } while (0)
; #define PG8_WAIT_V(n) asm volatile("s_waitcnt vmcnt(" #n ")" ::: "memory")
; #define PG8_WAIT_L(n) asm volatile("s_waitcnt lgkmcnt(" #n ")" ::: "memory")
; #define PG8_BAR __builtin_amdgcn_s_barrier()
; #define PG8_SCHED __builtin_amdgcn_sched_barrier(0)
; template <class Epi, class Sched, bool ALIGN_EPI = false, bool SP2 = false>
; __device__ __forceinline__ void gemm_phase(PG8_LAS unsigned char* lds, const Gemm g, const Sched& S, const Epi& E) {
;     ...
;             PG8_WAIT_V(8); PG8_WAIT_L(0); PG8_BAR; PG8_MMA(0, 0, At, B0); PG8_MMA(0, 1, At, B1); PG8_BAR; PG8_SCHED;
;             PG8_LDA(At, 0, 1); PG8_STAGE(PG8_SB(0, 0), b2, voffB); PG8_STAGE(PG8_SB(0, 1), b2 + hstep, voffB); PG8_STAGE(PG8_SA(0, 0), a2, voffA);
;             PG8_WAIT_V(8); PG8_WAIT_L(0); PG8_BAR; PG8_MMA(1, 0, At, B0); PG8_MMA(1, 1, At, B1); PG8_BAR; PG8_SCHED;
	s_setprio 1
	s_waitcnt lgkmcnt(0)
	v_mfma_f32_16x16x32_bf16 v[124:127], v[144:147], v[180:183], v[124:127]
	v_mfma_f32_16x16x32_bf16 v[116:119], v[152:155], v[180:183], v[116:119]
	v_mfma_f32_16x16x32_bf16 v[108:111], v[144:147], v[188:191], v[108:111]
	v_mfma_f32_16x16x32_bf16 v[100:103], v[152:155], v[188:191], v[100:103]
	v_mfma_f32_16x16x32_bf16 v[92:95], v[144:147], v[196:199], v[92:95]
	v_mfma_f32_16x16x32_bf16 v[84:87], v[152:155], v[196:199], v[84:87]
	v_mfma_f32_16x16x32_bf16 v[76:79], v[144:147], v[226:229], v[76:79]
	v_mfma_f32_16x16x32_bf16 v[68:71], v[152:155], v[226:229], v[68:71]
	v_mfma_f32_16x16x32_bf16 v[124:127], v[148:151], v[184:187], v[124:127]
	v_mfma_f32_16x16x32_bf16 v[116:119], v[156:159], v[184:187], v[116:119]
	v_mfma_f32_16x16x32_bf16 v[108:111], v[148:151], v[192:195], v[108:111]
	v_mfma_f32_16x16x32_bf16 v[100:103], v[156:159], v[192:195], v[100:103]
	v_mfma_f32_16x16x32_bf16 v[92:95], v[148:151], v[222:225], v[92:95]
	v_mfma_f32_16x16x32_bf16 v[84:87], v[156:159], v[222:225], v[84:87]
	v_mfma_f32_16x16x32_bf16 v[76:79], v[148:151], v[230:233], v[76:79]
	v_mfma_f32_16x16x32_bf16 v[68:71], v[156:159], v[230:233], v[68:71]
	s_setprio 0
	s_setprio 1
	v_mfma_f32_16x16x32_bf16 v[120:123], v[164:167], v[180:183], v[120:123]
	v_mfma_f32_16x16x32_bf16 v[112:115], v[172:175], v[180:183], v[112:115]
	v_mfma_f32_16x16x32_bf16 v[104:107], v[164:167], v[188:191], v[104:107]
	v_mfma_f32_16x16x32_bf16 v[96:99], v[172:175], v[188:191], v[96:99]
	v_mfma_f32_16x16x32_bf16 v[88:91], v[164:167], v[196:199], v[88:91]
	v_mfma_f32_16x16x32_bf16 v[80:83], v[172:175], v[196:199], v[80:83]
	v_mfma_f32_16x16x32_bf16 v[72:75], v[164:167], v[226:229], v[72:75]
	v_mfma_f32_16x16x32_bf16 v[64:67], v[172:175], v[226:229], v[64:67]
	v_mfma_f32_16x16x32_bf16 v[120:123], v[168:171], v[184:187], v[120:123]
	v_mfma_f32_16x16x32_bf16 v[112:115], v[176:179], v[184:187], v[112:115]
	v_mfma_f32_16x16x32_bf16 v[104:107], v[168:171], v[192:195], v[104:107]
	v_mfma_f32_16x16x32_bf16 v[96:99], v[176:179], v[192:195], v[96:99]
	v_mfma_f32_16x16x32_bf16 v[88:91], v[168:171], v[222:225], v[88:91]
	v_mfma_f32_16x16x32_bf16 v[80:83], v[176:179], v[222:225], v[80:83]
	v_mfma_f32_16x16x32_bf16 v[72:75], v[168:171], v[230:233], v[72:75]
	v_mfma_f32_16x16x32_bf16 v[64:67], v[176:179], v[230:233], v[64:67]
	s_setprio 0
	s_barrier
	s_add_i32 s76, s76, s24
	s_mov_b32 m0, s76
	ds_read_b128 v[180:183], v143 offset:16384
	ds_read_b128 v[184:187], v143 offset:17408
	ds_read_b128 v[188:191], v143 offset:18432
	ds_read_b128 v[192:195], v143 offset:19456
	ds_read_b128 v[196:199], v143 offset:20480
	ds_read_b128 v[222:225], v143 offset:21504
	ds_read_b128 v[226:229], v143 offset:22528
	ds_read_b128 v[230:233], v143 offset:23552
	global_load_lds_dwordx4 v160, s[4:5]
	s_add_i32 m0, s76, 0x2000
	s_add_u32 s76, s4, 0x80000
	s_addc_u32 s77, s5, 0
	s_add_i32 s78, s78, s24
	global_load_lds_dwordx4 v128, s[4:5]
	s_mov_b32 m0, s78
	s_nop 0
	global_load_lds_dwordx4 v160, s[76:77]
	s_add_i32 m0, s78, 0x2000
	s_nop 0
	global_load_lds_dwordx4 v128, s[76:77]
	s_mov_b32 m0, s51
	s_nop 0
	global_load_lds_dwordx4 v132, s[52:53]
	s_mov_b32 m0, s55
	s_nop 0
	global_load_lds_dwordx4 v130, s[52:53]
	s_add_u32 s98, s52, 0x80
	s_addc_u32 s99, s53, 0
	s_waitcnt vmcnt(8)
	s_waitcnt lgkmcnt(0)
	s_barrier
	s_setprio 1
	s_waitcnt lgkmcnt(0)
	v_mfma_f32_16x16x32_bf16 v[60:63], v[144:147], v[180:183], v[60:63]
	v_mfma_f32_16x16x32_bf16 v[52:55], v[152:155], v[180:183], v[52:55]
	v_mfma_f32_16x16x32_bf16 v[44:47], v[144:147], v[188:191], v[44:47]
	v_mfma_f32_16x16x32_bf16 v[36:39], v[152:155], v[188:191], v[36:39]
	v_mfma_f32_16x16x32_bf16 v[28:31], v[144:147], v[196:199], v[28:31]
	v_mfma_f32_16x16x32_bf16 v[20:23], v[152:155], v[196:199], v[20:23]
	v_mfma_f32_16x16x32_bf16 v[12:15], v[144:147], v[226:229], v[12:15]
	v_mfma_f32_16x16x32_bf16 v[4:7], v[152:155], v[226:229], v[4:7]
	v_mfma_f32_16x16x32_bf16 v[60:63], v[148:151], v[184:187], v[60:63]
	v_mfma_f32_16x16x32_bf16 v[52:55], v[156:159], v[184:187], v[52:55]
	v_mfma_f32_16x16x32_bf16 v[44:47], v[148:151], v[192:195], v[44:47]
	v_mfma_f32_16x16x32_bf16 v[36:39], v[156:159], v[192:195], v[36:39]
	v_mfma_f32_16x16x32_bf16 v[28:31], v[148:151], v[222:225], v[28:31]
	v_mfma_f32_16x16x32_bf16 v[20:23], v[156:159], v[222:225], v[20:23]
	v_mfma_f32_16x16x32_bf16 v[12:15], v[148:151], v[230:233], v[12:15]
	v_mfma_f32_16x16x32_bf16 v[4:7], v[156:159], v[230:233], v[4:7]
	s_setprio 0
	s_setprio 1
	v_mfma_f32_16x16x32_bf16 v[56:59], v[164:167], v[180:183], v[56:59]
	v_mfma_f32_16x16x32_bf16 v[48:51], v[172:175], v[180:183], v[48:51]
	v_mfma_f32_16x16x32_bf16 v[40:43], v[164:167], v[188:191], v[40:43]
	v_mfma_f32_16x16x32_bf16 v[32:35], v[172:175], v[188:191], v[32:35]
	v_mfma_f32_16x16x32_bf16 v[24:27], v[164:167], v[196:199], v[24:27]
	v_mfma_f32_16x16x32_bf16 v[16:19], v[172:175], v[196:199], v[16:19]
	v_mfma_f32_16x16x32_bf16 v[8:11], v[164:167], v[226:229], v[8:11]
	v_mfma_f32_16x16x32_bf16 v[0:3], v[172:175], v[226:229], v[0:3]
	v_mfma_f32_16x16x32_bf16 v[56:59], v[168:171], v[184:187], v[56:59]
	v_mfma_f32_16x16x32_bf16 v[48:51], v[176:179], v[184:187], v[48:51]
	v_mfma_f32_16x16x32_bf16 v[40:43], v[168:171], v[192:195], v[40:43]
	v_mfma_f32_16x16x32_bf16 v[32:35], v[176:179], v[192:195], v[32:35]
	v_mfma_f32_16x16x32_bf16 v[24:27], v[168:171], v[222:225], v[24:27]
	v_mfma_f32_16x16x32_bf16 v[16:19], v[176:179], v[222:225], v[16:19]
	v_mfma_f32_16x16x32_bf16 v[8:11], v[168:171], v[230:233], v[8:11]
	v_mfma_f32_16x16x32_bf16 v[0:3], v[176:179], v[230:233], v[0:3]
	s_setprio 0
	s_barrier
; #define PG8_STAGE(bufoff, gbase, voff) do { _Pragma("unroll") for (int _i = 0; _i < 2; ++_i) \
;         __builtin_amdgcn_global_load_lds((const unsigned*)((const char*)(gbase) + (voff)[_i]), (PG8_LAS unsigned*)(lds + (bufoff) + ldsw + _i * 8192), 16, 0, 0); } while (0)
; #define PG8_LDA(dst, b, h) do { _Pragma("unroll") for (int m = 0; m < 4; ++m) _Pragma("unroll") for (int k = 0; k < 2; ++k) dst[m][k] = *(const PG8_LAS bf16x8*)(lds + PG8_SA(b, h) + aoff + m * 2048 + k * 1024); } while (0)
; #define PG8_LDB(dst, b, h) do { _Pragma("unroll") for (int n = 0; n < 2; ++n) _Pragma("unroll") for (int k = 0; k < 2; ++k) dst[n][k] = *(const PG8_LAS bf16x8*)(lds + PG8_SB(b, h) + boff + n * 2048 + k * 1024); } while (0)
; #define PG8_MMA(ai, bj, At, Bt) do { __builtin_amdgcn_s_setprio(1); _Pragma("unroll") for (int m = 0; m < 4; ++m) _Pragma("unroll") for (int n = 0; n < 2; ++n) _Pragma("unroll") for (int k = 0; k < 2; ++k) \
;         acc[ai][bj][m][n] = __builtin_amdgcn_mfma_f32_16x16x32_bf16(Bt[n][k], At[m][k], acc[ai][bj][m][n], 0, 0, 0); __builtin_amdgcn_s_setprio(0); } while (0)
; #define PG8_WAIT_V(n) asm volatile("s_waitcnt vmcnt(" #n ")" ::: "memory")
; #define PG8_WAIT_L(n) asm volatile("s_waitcnt lgkmcnt(" #n ")" ::: "memory")
; #define PG8_BAR __builtin_amdgcn_s_barrier()
; #define PG8_SCHED __builtin_amdgcn_sched_barrier(0)
; template <class Epi, class Sched, bool ALIGN_EPI = false, bool SP2 = false>
; __device__ __forceinline__ void gemm_phase(PG8_LAS unsigned char* lds, const Gemm g, const Sched& S, const Epi& E) {
;     ...
;             PG8_LDB(B0, 1, 0); PG8_LDB(B1, 1, 1); PG8_SCHED; PG8_LDA(At, 1, 0); PG8_STAGE(PG8_SA(0, 1), a2 + hstep, voffA);
;             PG8_WAIT_V(8); PG8_WAIT_L(0); PG8_BAR; PG8_MMA(0, 0, At, B0); PG8_MMA(0, 1, At, B1); PG8_BAR; PG8_SCHED;
;             PG8_LDA(At, 1, 1); PG8_STAGE(PG8_SB(1, 0), b3, voffB); PG8_STAGE(PG8_SB(1, 1), b3 + hstep, voffB); PG8_STAGE(PG8_SA(1, 0), a3, voffA);
;             PG8_WAIT_V(8); PG8_WAIT_L(0); PG8_BAR; PG8_MMA(1, 0, At, B0); PG8_MMA(1, 1, At, B1); PG8_BAR; PG8_SCHED;
	s_add_i32 s76, 0, 0x18000
	s_add_i32 s77, 0, 0x1c000
	ds_read_b128 v[144:147], v200 offset:32768
	ds_read_b128 v[148:151], v200 offset:33792
	ds_read_b128 v[152:155], v200 offset:34816
	ds_read_b128 v[156:159], v200 offset:35840
	ds_read_b128 v[164:167], v200 offset:49152
	ds_read_b128 v[168:171], v200 offset:50176
	ds_read_b128 v[172:175], v200 offset:51200
	ds_read_b128 v[176:179], v200 offset:52224
	s_add_u32 s52, s52, 0x80000
	s_addc_u32 s53, s53, 0
	s_mov_b32 m0, s56
	ds_read_b128 v[180:183], v143 offset:32768
	ds_read_b128 v[184:187], v143 offset:33792
	ds_read_b128 v[188:191], v143 offset:34816
	ds_read_b128 v[192:195], v143 offset:35840
	ds_read_b128 v[196:199], v143 offset:36864
	ds_read_b128 v[222:225], v143 offset:37888
	ds_read_b128 v[226:229], v143 offset:38912
	ds_read_b128 v[230:233], v143 offset:39936
	global_load_lds_dwordx4 v132, s[52:53]
	s_mov_b32 m0, s57
	s_nop 0
	global_load_lds_dwordx4 v130, s[52:53]
	s_waitcnt vmcnt(8)
	s_waitcnt lgkmcnt(0)
	s_barrier
	s_setprio 1
	s_waitcnt lgkmcnt(0)
	v_mfma_f32_16x16x32_bf16 v[124:127], v[144:147], v[180:183], v[124:127]
	v_mfma_f32_16x16x32_bf16 v[116:119], v[152:155], v[180:183], v[116:119]
	v_mfma_f32_16x16x32_bf16 v[108:111], v[144:147], v[188:191], v[108:111]
	v_mfma_f32_16x16x32_bf16 v[100:103], v[152:155], v[188:191], v[100:103]
	v_mfma_f32_16x16x32_bf16 v[92:95], v[144:147], v[196:199], v[92:95]
	v_mfma_f32_16x16x32_bf16 v[84:87], v[152:155], v[196:199], v[84:87]
	v_mfma_f32_16x16x32_bf16 v[76:79], v[144:147], v[226:229], v[76:79]
	v_mfma_f32_16x16x32_bf16 v[68:71], v[152:155], v[226:229], v[68:71]
	v_mfma_f32_16x16x32_bf16 v[124:127], v[148:151], v[184:187], v[124:127]
	v_mfma_f32_16x16x32_bf16 v[116:119], v[156:159], v[184:187], v[116:119]
	v_mfma_f32_16x16x32_bf16 v[108:111], v[148:151], v[192:195], v[108:111]
	v_mfma_f32_16x16x32_bf16 v[100:103], v[156:159], v[192:195], v[100:103]
	v_mfma_f32_16x16x32_bf16 v[92:95], v[148:151], v[222:225], v[92:95]
	v_mfma_f32_16x16x32_bf16 v[84:87], v[156:159], v[222:225], v[84:87]
	v_mfma_f32_16x16x32_bf16 v[76:79], v[148:151], v[230:233], v[76:79]
	v_mfma_f32_16x16x32_bf16 v[68:71], v[156:159], v[230:233], v[68:71]
	s_setprio 0
	s_setprio 1
	v_mfma_f32_16x16x32_bf16 v[120:123], v[164:167], v[180:183], v[120:123]
	v_mfma_f32_16x16x32_bf16 v[112:115], v[172:175], v[180:183], v[112:115]
	v_mfma_f32_16x16x32_bf16 v[104:107], v[164:167], v[188:191], v[104:107]
	v_mfma_f32_16x16x32_bf16 v[96:99], v[172:175], v[188:191], v[96:99]
	v_mfma_f32_16x16x32_bf16 v[88:91], v[164:167], v[196:199], v[88:91]
	v_mfma_f32_16x16x32_bf16 v[80:83], v[172:175], v[196:199], v[80:83]
	v_mfma_f32_16x16x32_bf16 v[72:75], v[164:167], v[226:229], v[72:75]
	v_mfma_f32_16x16x32_bf16 v[64:67], v[172:175], v[226:229], v[64:67]
	v_mfma_f32_16x16x32_bf16 v[120:123], v[168:171], v[184:187], v[120:123]
	v_mfma_f32_16x16x32_bf16 v[112:115], v[176:179], v[184:187], v[112:115]
	v_mfma_f32_16x16x32_bf16 v[104:107], v[168:171], v[192:195], v[104:107]
	v_mfma_f32_16x16x32_bf16 v[96:99], v[176:179], v[192:195], v[96:99]
	v_mfma_f32_16x16x32_bf16 v[88:91], v[168:171], v[222:225], v[88:91]
	v_mfma_f32_16x16x32_bf16 v[80:83], v[176:179], v[222:225], v[80:83]
	v_mfma_f32_16x16x32_bf16 v[72:75], v[168:171], v[230:233], v[72:75]
	v_mfma_f32_16x16x32_bf16 v[64:67], v[176:179], v[230:233], v[64:67]
	s_setprio 0
	s_barrier
	s_add_i32 s52, s76, s24
	s_mov_b32 m0, s52
	ds_read_b128 v[180:183], v143 offset:49152
	ds_read_b128 v[184:187], v143 offset:50176
	ds_read_b128 v[188:191], v143 offset:51200
	ds_read_b128 v[192:195], v143 offset:52224
	ds_read_b128 v[196:199], v143 offset:53248
	ds_read_b128 v[222:225], v143 offset:54272
	ds_read_b128 v[226:229], v143 offset:55296
	ds_read_b128 v[230:233], v143 offset:56320
	s_add_u32 s4, s4, 0x80
	s_addc_u32 s5, s5, 0
	global_load_lds_dwordx4 v160, s[4:5]
	s_add_i32 m0, s52, 0x2000
	s_add_i32 s52, s77, s24
	global_load_lds_dwordx4 v128, s[4:5]
	s_add_u32 s4, s4, 0x80000
	s_addc_u32 s5, s5, 0
	s_mov_b32 m0, s52
	s_nop 0
	global_load_lds_dwordx4 v160, s[4:5]
	s_add_i32 m0, s52, 0x2000
	s_nop 0
	global_load_lds_dwordx4 v128, s[4:5]
	s_mov_b32 m0, s58
	s_nop 0
	global_load_lds_dwordx4 v132, s[98:99]
	s_mov_b32 m0, s59
	s_nop 0
	global_load_lds_dwordx4 v130, s[98:99]
	s_waitcnt vmcnt(8)
	s_waitcnt lgkmcnt(0)
	s_barrier
	s_setprio 1
	s_waitcnt lgkmcnt(0)
	v_mfma_f32_16x16x32_bf16 v[60:63], v[144:147], v[180:183], v[60:63]
	v_mfma_f32_16x16x32_bf16 v[52:55], v[152:155], v[180:183], v[52:55]
	v_mfma_f32_16x16x32_bf16 v[44:47], v[144:147], v[188:191], v[44:47]
	v_mfma_f32_16x16x32_bf16 v[36:39], v[152:155], v[188:191], v[36:39]
	v_mfma_f32_16x16x32_bf16 v[28:31], v[144:147], v[196:199], v[28:31]
	v_mfma_f32_16x16x32_bf16 v[20:23], v[152:155], v[196:199], v[20:23]
	v_mfma_f32_16x16x32_bf16 v[12:15], v[144:147], v[226:229], v[12:15]
	v_mfma_f32_16x16x32_bf16 v[4:7], v[152:155], v[226:229], v[4:7]
	v_mfma_f32_16x16x32_bf16 v[60:63], v[148:151], v[184:187], v[60:63]
	v_mfma_f32_16x16x32_bf16 v[52:55], v[156:159], v[184:187], v[52:55]
	v_mfma_f32_16x16x32_bf16 v[44:47], v[148:151], v[192:195], v[44:47]
	v_mfma_f32_16x16x32_bf16 v[36:39], v[156:159], v[192:195], v[36:39]
	v_mfma_f32_16x16x32_bf16 v[28:31], v[148:151], v[222:225], v[28:31]
	v_mfma_f32_16x16x32_bf16 v[20:23], v[156:159], v[222:225], v[20:23]
	v_mfma_f32_16x16x32_bf16 v[12:15], v[148:151], v[230:233], v[12:15]
	v_mfma_f32_16x16x32_bf16 v[4:7], v[156:159], v[230:233], v[4:7]
	s_setprio 0
	s_setprio 1
	v_mfma_f32_16x16x32_bf16 v[56:59], v[164:167], v[180:183], v[56:59]
	v_mfma_f32_16x16x32_bf16 v[48:51], v[172:175], v[180:183], v[48:51]
	v_mfma_f32_16x16x32_bf16 v[40:43], v[164:167], v[188:191], v[40:43]
	v_mfma_f32_16x16x32_bf16 v[32:35], v[172:175], v[188:191], v[32:35]
	v_mfma_f32_16x16x32_bf16 v[24:27], v[164:167], v[196:199], v[24:27]
	v_mfma_f32_16x16x32_bf16 v[16:19], v[172:175], v[196:199], v[16:19]
	v_mfma_f32_16x16x32_bf16 v[8:11], v[164:167], v[226:229], v[8:11]
	v_mfma_f32_16x16x32_bf16 v[0:3], v[172:175], v[226:229], v[0:3]
	v_mfma_f32_16x16x32_bf16 v[56:59], v[168:171], v[184:187], v[56:59]
	v_mfma_f32_16x16x32_bf16 v[48:51], v[176:179], v[184:187], v[48:51]
	v_mfma_f32_16x16x32_bf16 v[40:43], v[168:171], v[192:195], v[40:43]
	v_mfma_f32_16x16x32_bf16 v[32:35], v[176:179], v[192:195], v[32:35]
	v_mfma_f32_16x16x32_bf16 v[24:27], v[168:171], v[222:225], v[24:27]
	v_mfma_f32_16x16x32_bf16 v[16:19], v[176:179], v[222:225], v[16:19]
	v_mfma_f32_16x16x32_bf16 v[8:11], v[168:171], v[230:233], v[8:11]
	v_mfma_f32_16x16x32_bf16 v[0:3], v[176:179], v[230:233], v[0:3]
	s_setprio 0
	s_barrier
	s_add_i32 s75, s75, 2
	s_add_u32 s70, s70, 0x100
	s_addc_u32 s71, s71, 0
	s_add_u32 s73, s73, 0x100
	s_addc_u32 s74, s74, 0
	s_cmp_gt_u32 s75, 29
	s_cbranch_scc0 .LBB0_849
	s_and_b64 vcc, exec, s[8:9]
	s_cbranch_vccz .LBB0_852
	s_barrier
